# C item outputs transposed through LDS (dead xhatT image, XOR-swizzled) so four consecutive lanes store one 64-byte row segment: 8 coalesced dwordx4 stores per lane
# speedup vs baseline: 1.0170x; 1.0049x over previous
.LBB0_779:
	v_mov_b32_e32 v43, v0
	s_ashr_i32 s5, s3, 31
	v_ashrrev_i32_e32 v44, 7, v43
	s_waitcnt vmcnt(2)
	v_add_u32_e32 v164, s2, v44
	v_ashrrev_i32_e32 v165, 31, v164
	v_and_b32_e32 v168, 31, v43
	s_waitcnt vmcnt(0)
	v_lshlrev_b64 v[2:3], 15, v[164:165]
	v_bfe_u32 v169, v43, 5, 1
	v_lshl_add_u64 v[2:3], s[56:57], 0, v[2:3]
	v_lshlrev_b32_e32 v154, 8, v168
	v_lshl_add_u64 v[2:3], v[2:3], 0, v[154:155]
	v_lshlrev_b32_e32 v154, 4, v169
	v_lshl_add_u64 v[18:19], v[2:3], 0, v[154:155]
	v_add_co_u32_e32 v20, vcc, s14, v18
	v_ashrrev_i32_e32 v45, 2, v43
	s_nop 0
	v_addc_co_u32_e32 v21, vcc, 0, v19, vcc
	v_add_co_u32_e32 v22, vcc, s17, v18
	global_load_dwordx4 v[2:5], v[18:19], off
	global_load_dwordx4 v[6:9], v[20:21], off
	v_addc_co_u32_e32 v23, vcc, 0, v19, vcc
	v_add_co_u32_e32 v24, vcc, s30, v18
	global_load_dwordx4 v[10:13], v[22:23], off
	s_nop 0
	v_addc_co_u32_e32 v25, vcc, 0, v19, vcc
	global_load_dwordx4 v[14:17], v[24:25], off
	global_load_dwordx4 v[138:141], v[18:19], off offset:32
	global_load_dwordx4 v[142:145], v[20:21], off offset:32
	global_load_dwordx4 v[146:149], v[22:23], off offset:32
	global_load_dwordx4 v[150:153], v[24:25], off offset:32
	global_load_dwordx4 v[126:129], v[20:21], off offset:64
	global_load_dwordx4 v[130:133], v[22:23], off offset:64
	global_load_dwordx4 v[134:137], v[24:25], off offset:64
	global_load_dwordx4 v[114:117], v[20:21], off offset:96
	global_load_dwordx4 v[118:121], v[22:23], off offset:96
	global_load_dwordx4 v[122:125], v[24:25], off offset:96
	global_load_dwordx4 v[106:109], v[22:23], off offset:128
	global_load_dwordx4 v[110:113], v[24:25], off offset:128
	global_load_dwordx4 v[98:101], v[22:23], off offset:160
	global_load_dwordx4 v[102:105], v[24:25], off offset:160
	global_load_dwordx4 v[94:97], v[24:25], off offset:192
	global_load_dwordx4 v[90:93], v[24:25], off offset:224
	v_add_u32_e32 v18, s3, v45
	v_ashrrev_i32_e32 v19, 31, v18
	v_lshlrev_b32_e32 v20, 6, v43
	v_lshlrev_b64 v[18:19], 12, v[18:19]
	v_and_b32_e32 v46, 0xc0, v20
	v_lshl_add_u64 v[18:19], s[60:61], 0, v[18:19]
	v_lshlrev_b32_e32 v20, 1, v46
	v_mov_b32_e32 v21, v155
	v_lshl_add_u64 v[34:35], v[18:19], 0, v[20:21]
	global_load_dwordx4 v[18:21], v[34:35], off offset:3632
	global_load_dwordx4 v[22:25], v[34:35], off offset:3616
	global_load_dwordx4 v[26:29], v[34:35], off offset:3600
	global_load_dwordx4 v[30:33], v[34:35], off offset:3584
	global_load_dwordx4 v[36:39], v[34:35], off offset:3680
	global_load_dwordx4 v[202:205], v[34:35], off offset:3664
	global_load_dwordx4 v[48:51], v[34:35], off offset:3648
	global_load_dwordx4 v[206:209], v[34:35], off offset:3696
	v_and_b32_e32 v215, 31, v0
	v_add_u32_e32 v215, s3, v215
	v_lshlrev_b32_e32 v215, 12, v215
	v_and_b32_e32 v245, 0x1c0, v0
	v_add_u32_e32 v215, v215, v245
	v_bfe_u32 v245, v0, 5, 1
	v_lshl_add_u32 v245, v245, 3, v215
	v_bfe_u32 v215, v0, 5, 1
	v_lshl_add_u32 v215, v215, 3, v245
	global_load_dwordx4 v[216:219], v215, s[60:61] offset:3072
	global_load_dwordx4 v[220:223], v215, s[60:61] offset:3104
	s_add_u32 s98, s60, 0x20000
	s_addc_u32 s99, s61, 0
	global_load_dwordx4 v[224:227], v215, s[98:99] offset:3072
	global_load_dwordx4 v[228:231], v215, s[98:99] offset:3104
	s_add_u32 s100, s60, 0x40000
	s_addc_u32 s101, s61, 0
	global_load_dwordx4 v[232:235], v215, s[100:101] offset:3072
	global_load_dwordx4 v[236:239], v215, s[100:101] offset:3104
	s_add_u32 s98, s60, 0x60000
	s_addc_u32 s99, s61, 0
	global_load_dwordx4 v[252:255], v215, s[98:99] offset:3072
	global_load_dwordx2 v[240:241], v245, s[98:99] offset:3104
	global_load_dwordx2 v[246:247], v245, s[98:99] offset:3120
	v_lshrrev_b32_e32 v42, 5, v43
	s_add_i32 s4, s4, s46
	s_waitcnt vmcnt(16)
	v_lshlrev_b32_e32 v178, 16, v18
	s_waitcnt vmcnt(15)
	v_lshlrev_b32_e32 v186, 16, v22
	s_waitcnt vmcnt(14)
	v_lshlrev_b32_e32 v194, 16, v26
	s_waitcnt vmcnt(13)
	v_lshlrev_b32_e32 v200, 16, v30
	v_and_b32_e32 v199, 0xffff0000, v30
	v_add_f32_e32 v30, 0, v200
	v_lshlrev_b32_e32 v198, 16, v31
	v_add_f32_e32 v30, v30, v199
	v_and_b32_e32 v197, 0xffff0000, v31
	v_mul_f32_e32 v31, v199, v199
	v_add_f32_e32 v30, v30, v198
	v_lshlrev_b32_e32 v196, 16, v32
	v_fmac_f32_e32 v31, v200, v200
	v_add_f32_e32 v30, v30, v197
	v_and_b32_e32 v195, 0xffff0000, v32
	v_fmac_f32_e32 v31, v198, v198
	v_add_f32_e32 v30, v30, v196
	v_lshlrev_b32_e32 v193, 16, v33
	v_fmac_f32_e32 v31, v197, v197
	v_add_f32_e32 v30, v30, v195
	v_and_b32_e32 v191, 0xffff0000, v33
	v_fmac_f32_e32 v31, v196, v196
	v_add_f32_e32 v30, v30, v193
	v_fmac_f32_e32 v31, v195, v195
	v_add_f32_e32 v30, v30, v191
	v_fmac_f32_e32 v31, v193, v193
	v_and_b32_e32 v192, 0xffff0000, v26
	v_add_f32_e32 v26, v30, v194
	v_fmac_f32_e32 v31, v191, v191
	v_lshlrev_b32_e32 v190, 16, v27
	v_add_f32_e32 v26, v26, v192
	v_and_b32_e32 v189, 0xffff0000, v27
	v_fmac_f32_e32 v31, v194, v194
	v_add_f32_e32 v26, v26, v190
	v_lshlrev_b32_e32 v188, 16, v28
	v_fmac_f32_e32 v31, v192, v192
	v_add_f32_e32 v26, v26, v189
	v_and_b32_e32 v187, 0xffff0000, v28
	v_fmac_f32_e32 v31, v190, v190
	v_add_f32_e32 v26, v26, v188
	v_lshlrev_b32_e32 v184, 16, v29
	v_fmac_f32_e32 v31, v189, v189
	v_add_f32_e32 v26, v26, v187
	v_and_b32_e32 v182, 0xffff0000, v29
	v_fmac_f32_e32 v31, v188, v188
	v_add_f32_e32 v26, v26, v184
	v_fmac_f32_e32 v31, v187, v187
	v_add_f32_e32 v26, v26, v182
	v_fmac_f32_e32 v31, v184, v184
	v_and_b32_e32 v185, 0xffff0000, v22
	v_add_f32_e32 v22, v26, v186
	v_fmac_f32_e32 v31, v182, v182
	v_lshlrev_b32_e32 v183, 16, v23
	v_add_f32_e32 v22, v22, v185
	v_and_b32_e32 v179, 0xffff0000, v23
	v_fmac_f32_e32 v31, v186, v186
	v_add_f32_e32 v22, v22, v183
	v_lshlrev_b32_e32 v177, 16, v24
	v_fmac_f32_e32 v31, v185, v185
	v_add_f32_e32 v22, v22, v179
	v_and_b32_e32 v175, 0xffff0000, v24
	v_fmac_f32_e32 v31, v183, v183
	v_add_f32_e32 v22, v22, v177
	v_lshlrev_b32_e32 v173, 16, v25
	v_fmac_f32_e32 v31, v179, v179
	v_add_f32_e32 v22, v22, v175
	v_and_b32_e32 v171, 0xffff0000, v25
	v_fmac_f32_e32 v31, v177, v177
	v_add_f32_e32 v22, v22, v173
	v_fmac_f32_e32 v31, v175, v175
	v_add_f32_e32 v22, v22, v171
	v_fmac_f32_e32 v31, v173, v173
	v_and_b32_e32 v176, 0xffff0000, v18
	v_add_f32_e32 v18, v22, v178
	v_fmac_f32_e32 v31, v171, v171
	v_lshlrev_b32_e32 v174, 16, v19
	v_add_f32_e32 v18, v18, v176
	v_and_b32_e32 v172, 0xffff0000, v19
	v_fmac_f32_e32 v31, v178, v178
	v_add_f32_e32 v18, v18, v174
	v_lshlrev_b32_e32 v167, 16, v20
	v_fmac_f32_e32 v31, v176, v176
	v_add_f32_e32 v18, v18, v172
	v_and_b32_e32 v165, 0xffff0000, v20
	v_fmac_f32_e32 v31, v174, v174
	v_add_f32_e32 v18, v18, v167
	v_lshlrev_b32_e32 v64, 16, v21
	v_fmac_f32_e32 v31, v172, v172
	v_add_f32_e32 v18, v18, v165
	v_and_b32_e32 v62, 0xffff0000, v21
	v_fmac_f32_e32 v31, v167, v167
	v_add_f32_e32 v18, v18, v64
	v_fmac_f32_e32 v31, v165, v165
	v_add_f32_e32 v18, v18, v62
	s_waitcnt vmcnt(10)
	v_lshlrev_b32_e32 v170, 16, v48
	v_fmac_f32_e32 v31, v64, v64
	v_and_b32_e32 v166, 0xffff0000, v48
	v_add_f32_e32 v18, v18, v170
	v_fmac_f32_e32 v31, v62, v62
	v_lshlrev_b32_e32 v65, 16, v49
	v_add_f32_e32 v18, v18, v166
	v_and_b32_e32 v63, 0xffff0000, v49
	v_fmac_f32_e32 v31, v170, v170
	v_add_f32_e32 v18, v18, v65
	v_lshlrev_b32_e32 v60, 16, v50
	v_fmac_f32_e32 v31, v166, v166
	v_add_f32_e32 v18, v18, v63
	v_and_b32_e32 v59, 0xffff0000, v50
	v_fmac_f32_e32 v31, v65, v65
	v_add_f32_e32 v18, v18, v60
	v_lshlrev_b32_e32 v57, 16, v51
	v_fmac_f32_e32 v31, v63, v63
	v_add_f32_e32 v18, v18, v59
	v_and_b32_e32 v55, 0xffff0000, v51
	v_fmac_f32_e32 v31, v60, v60
	v_add_f32_e32 v18, v18, v57
	v_fmac_f32_e32 v31, v59, v59
	v_add_f32_e32 v18, v18, v55
	v_lshlrev_b32_e32 v61, 16, v202
	v_fmac_f32_e32 v31, v57, v57
	v_and_b32_e32 v58, 0xffff0000, v202
	v_add_f32_e32 v18, v18, v61
	v_fmac_f32_e32 v31, v55, v55
	v_lshlrev_b32_e32 v56, 16, v203
	v_add_f32_e32 v18, v18, v58
	v_and_b32_e32 v54, 0xffff0000, v203
	v_fmac_f32_e32 v31, v61, v61
	v_add_f32_e32 v18, v18, v56
	v_lshlrev_b32_e32 v53, 16, v204
	v_fmac_f32_e32 v31, v58, v58
	v_add_f32_e32 v18, v18, v54
	v_and_b32_e32 v51, 0xffff0000, v204
	v_fmac_f32_e32 v31, v56, v56
	v_add_f32_e32 v18, v18, v53
	v_lshlrev_b32_e32 v49, 16, v205
	v_fmac_f32_e32 v31, v54, v54
	v_add_f32_e32 v18, v18, v51
	v_and_b32_e32 v47, 0xffff0000, v205
	v_fmac_f32_e32 v31, v53, v53
	v_add_f32_e32 v18, v18, v49
	v_fmac_f32_e32 v31, v51, v51
	v_add_f32_e32 v18, v18, v47
	v_lshlrev_b32_e32 v52, 16, v36
	v_fmac_f32_e32 v31, v49, v49
	v_and_b32_e32 v50, 0xffff0000, v36
	v_add_f32_e32 v18, v18, v52
	v_fmac_f32_e32 v31, v47, v47
	v_lshlrev_b32_e32 v48, 16, v37
	v_add_f32_e32 v18, v18, v50
	v_fmac_f32_e32 v31, v52, v52
	v_add_f32_e32 v18, v18, v48
	v_and_b32_e32 v37, 0xffff0000, v37
	v_fmac_f32_e32 v31, v50, v50
	v_lshlrev_b32_e32 v34, 16, v38
	v_mov_b32_e32 v35, v37
	v_add_f32_e32 v20, v18, v37
	v_fmac_f32_e32 v31, v48, v48
	v_and_b32_e32 v24, 0xffff0000, v38
	v_pk_mul_f32 v[18:19], v[34:35], v[34:35]
	v_add_f32_e32 v20, v20, v34
	v_lshlrev_b32_e32 v25, 16, v39
	v_add_f32_e32 v19, v19, v31
	v_add_f32_e32 v20, v20, v24
	v_add_f32_e32 v21, v18, v19
	v_pk_mul_f32 v[18:19], v[24:25], v[24:25]
	v_add_f32_e32 v20, v20, v25
	v_and_b32_e32 v33, 0xffff0000, v39
	v_add_f32_e32 v18, v18, v21
	s_waitcnt vmcnt(9)
	v_lshlrev_b32_e32 v28, 16, v206
	v_mov_b32_e32 v29, v33
	v_add_f32_e32 v20, v20, v33
	v_add_f32_e32 v21, v19, v18
	v_and_b32_e32 v22, 0xffff0000, v206
	v_pk_mul_f32 v[18:19], v[28:29], v[28:29]
	v_add_f32_e32 v20, v20, v28
	v_lshlrev_b32_e32 v23, 16, v207
	v_add_f32_e32 v19, v19, v21
	v_add_f32_e32 v20, v20, v22
	v_add_f32_e32 v21, v18, v19
	v_pk_mul_f32 v[18:19], v[22:23], v[22:23]
	v_add_f32_e32 v29, v20, v23
	v_and_b32_e32 v31, 0xffff0000, v207
	v_add_f32_e32 v18, v18, v21
	v_lshlrev_b32_e32 v26, 16, v208
	v_mov_b32_e32 v27, v31
	v_add_f32_e32 v29, v29, v31
	v_and_b32_e32 v36, s0, v38
	v_add_f32_e32 v18, v19, v18
	v_and_b32_e32 v20, 0xffff0000, v208
	v_pk_mul_f32 v[38:39], v[26:27], v[26:27]
	v_add_f32_e32 v27, v29, v26
	v_lshlrev_b32_e32 v21, 16, v209
	v_add_f32_e32 v18, v39, v18
	v_add_f32_e32 v27, v27, v20
	v_and_b32_e32 v29, 64, v181
	v_add_f32_e32 v18, v38, v18
	v_pk_mul_f32 v[40:41], v[20:21], v[20:21]
	v_add_f32_e32 v39, v27, v21
	v_xor_b32_e32 v27, 1, v181
	v_add_u32_e32 v29, 64, v29
	v_and_b32_e32 v19, 0xffff0000, v209
	v_add_f32_e32 v18, v40, v18
	v_cmp_lt_i32_e32 vcc, v27, v29
	v_add_f32_e32 v18, v41, v18
	v_mul_f32_e32 v38, v19, v19
	v_cndmask_b32_e32 v27, v181, v27, vcc
	v_lshlrev_b32_e32 v27, 2, v27
	v_pk_add_f32 v[38:39], v[38:39], v[18:19]
	ds_bpermute_b32 v41, v27, v39
	ds_bpermute_b32 v40, v27, v38
	v_xor_b32_e32 v35, 2, v181
	v_cmp_lt_i32_e32 vcc, v35, v29
	v_and_b32_e32 v30, s0, v206
	v_mov_b32_e32 v32, v36
	v_cndmask_b32_e32 v29, v181, v35, vcc
	v_lshlrev_b32_e32 v29, 2, v29
	s_waitcnt lgkmcnt(0)
	v_pk_add_f32 v[38:39], v[38:39], v[40:41]
	ds_bpermute_b32 v41, v29, v39
	ds_bpermute_b32 v40, v29, v38
	s_waitcnt lgkmcnt(0)
	v_pk_add_f32 v[40:41], v[38:39], v[40:41]
	s_nop 0
	v_pk_mul_f32 v[38:39], v[40:41], s[22:23] op_sel_hi:[1,0]
	v_pk_fma_f32 v[36:37], v[40:41], s[22:23], v[36:37] op_sel_hi:[1,0,1] neg_lo:[1,0,0] neg_hi:[1,0,0]
	v_fma_f32 v18, -v39, v39, v38
	v_max_f32_e32 v18, 0, v18
	v_add_f32_e32 v18, 0x358637bd, v18
	v_cmp_gt_f32_e32 vcc, s33, v18
	v_mul_f32_e32 v27, 0x4b800000, v18
	v_sub_f32_e32 v29, v200, v39
	v_cndmask_b32_e32 v18, v18, v27, vcc
	v_rsq_f32_e32 v18, v18
	v_sub_f32_e32 v19, v19, v39
	v_mul_f32_e32 v27, 0x45800000, v18
	v_cndmask_b32_e32 v18, v18, v27, vcc
	v_mul_f32_e32 v29, v29, v18
	v_lshlrev_b32_e32 v27, 1, v45
	v_bfe_u32 v35, v29, 16, 1
	v_ashrrev_i32_e32 v45, 1, v43
	v_and_b32_e32 v27, 14, v27
	v_add3_u32 v29, v29, v35, s15
	v_lshl_add_u32 v35, v46, 8, 32
	v_and_b32_e32 v46, -16, v45
	v_add3_u32 v200, v35, v46, v27
	ds_write_b16_d16_hi v200, v29 offset:55296
	v_mul_f32_e64 v215, -v39, v18
	v_fma_f32 v29, v199, v18, v215
	v_cvt_pk_bf16_f32 v29, v29, v29
	v_bitop3_b32 v199, v45, 16, -16 bitop3:0x6c
	v_add3_u32 v201, v35, v199, v27
	ds_write_b16 v201, v29 offset:55552
	v_fma_f32 v29, v198, v18, v215
	v_cvt_pk_bf16_f32 v29, v29, v29
	v_bitop3_b32 v198, v45, 32, -16 bitop3:0x6c
	v_add3_u32 v202, v35, v198, v27
	ds_write_b16 v202, v29 offset:55808
	v_fma_f32 v29, v197, v18, v215
	v_cvt_pk_bf16_f32 v29, v29, v29
	v_bitop3_b32 v197, v45, 48, -16 bitop3:0x6c
	v_add3_u32 v203, v35, v197, v27
	ds_write_b16 v203, v29 offset:56064
	v_fma_f32 v29, v196, v18, v215
	v_cvt_pk_bf16_f32 v29, v29, v29
	v_bitop3_b32 v196, v45, 64, -16 bitop3:0x6c
	v_add3_u32 v204, v35, v196, v27
	ds_write_b16 v204, v29 offset:56320
	v_fma_f32 v29, v195, v18, v215
	v_cvt_pk_bf16_f32 v29, v29, v29
	v_bitop3_b32 v195, v45, s34, -16 bitop3:0x6c
	v_add3_u32 v205, v35, v195, v27
	ds_write_b16 v205, v29 offset:56576
	v_fma_f32 v29, v193, v18, v215
	v_cvt_pk_bf16_f32 v29, v29, v29
	v_bitop3_b32 v193, v45, s31, -16 bitop3:0x6c
	v_add3_u32 v206, v35, v193, v27
	ds_write_b16 v206, v29 offset:56832
	v_fma_f32 v29, v191, v18, v215
	v_cvt_pk_bf16_f32 v29, v29, v29
	v_bitop3_b32 v191, v45, s13, -16 bitop3:0x6c
	v_add3_u32 v207, v35, v191, v27
	ds_write_b16 v207, v29 offset:57088
	v_fma_f32 v29, v194, v18, v215
	v_cvt_pk_bf16_f32 v29, v29, v29
	v_bitop3_b32 v194, v45, s12, -16 bitop3:0x6c
	v_add3_u32 v208, v35, v194, v27
	ds_write_b16 v208, v29 offset:57344
	v_fma_f32 v29, v192, v18, v215
	v_cvt_pk_bf16_f32 v29, v29, v29
	v_bitop3_b32 v192, v45, s35, -16 bitop3:0x6c
	v_add3_u32 v209, v35, v192, v27
	ds_write_b16 v209, v29 offset:57600
	v_fma_f32 v29, v190, v18, v215
	v_cvt_pk_bf16_f32 v29, v29, v29
	v_bitop3_b32 v190, v45, s36, -16 bitop3:0x6c
	v_add3_u32 v210, v35, v190, v27
	ds_write_b16 v210, v29 offset:57856
	v_fma_f32 v29, v189, v18, v215
	v_cvt_pk_bf16_f32 v29, v29, v29
	v_bitop3_b32 v189, v45, s37, -16 bitop3:0x6c
	v_add3_u32 v211, v35, v189, v27
	ds_write_b16 v211, v29 offset:58112
	v_fma_f32 v29, v188, v18, v215
	v_cvt_pk_bf16_f32 v29, v29, v29
	v_bitop3_b32 v188, v45, s16, -16 bitop3:0x6c
	v_add3_u32 v212, v35, v188, v27
	ds_write_b16 v212, v29 offset:58368
	v_fma_f32 v29, v187, v18, v215
	v_cvt_pk_bf16_f32 v29, v29, v29
	v_bitop3_b32 v187, v45, s42, -16 bitop3:0x6c
	v_add3_u32 v213, v35, v187, v27
	ds_write_b16 v213, v29 offset:58624
	v_fma_f32 v29, v184, v18, v215
	v_cvt_pk_bf16_f32 v29, v29, v29
	v_bitop3_b32 v184, v45, s43, -16 bitop3:0x6c
	v_add3_u32 v214, v35, v184, v27
	ds_write_b16 v214, v29 offset:58880
	v_sub_f32_e32 v29, v182, v39
	v_mul_f32_e32 v29, v29, v18
	v_bfe_u32 v182, v29, 16, 1
	v_bitop3_b32 v45, v45, s94, -16 bitop3:0x6c
	v_add_u32_e32 v38, 0xd800, v35
	v_add3_u32 v29, v29, v182, s15
	v_add3_u32 v35, v35, v45, v27
	ds_write_b16_d16_hi v35, v29 offset:59136
	v_fma_f32 v29, v186, v18, v215
	v_cvt_pk_bf16_f32 v29, v29, v29
	ds_write_b16 v200, v29 offset:59392
	v_fma_f32 v29, v185, v18, v215
	v_cvt_pk_bf16_f32 v29, v29, v29
	ds_write_b16 v201, v29 offset:59648
	v_fma_f32 v29, v183, v18, v215
	v_cvt_pk_bf16_f32 v29, v29, v29
	ds_write_b16 v202, v29 offset:59904
	v_fma_f32 v29, v179, v18, v215
	v_cvt_pk_bf16_f32 v29, v29, v29
	ds_write_b16 v203, v29 offset:60160
	v_fma_f32 v29, v177, v18, v215
	v_cvt_pk_bf16_f32 v29, v29, v29
	ds_write_b16 v204, v29 offset:60416
	v_fma_f32 v29, v175, v18, v215
	v_cvt_pk_bf16_f32 v29, v29, v29
	ds_write_b16 v205, v29 offset:60672
	v_fma_f32 v29, v173, v18, v215
	v_cvt_pk_bf16_f32 v29, v29, v29
	ds_write_b16 v206, v29 offset:60928
	v_fma_f32 v29, v171, v18, v215
	v_cvt_pk_bf16_f32 v29, v29, v29
	ds_write_b16 v207, v29 offset:61184
	v_fma_f32 v29, v178, v18, v215
	v_cvt_pk_bf16_f32 v29, v29, v29
	ds_write_b16 v208, v29 offset:61440
	v_fma_f32 v29, v176, v18, v215
	v_cvt_pk_bf16_f32 v29, v29, v29
	ds_write_b16 v209, v29 offset:61696
	v_fma_f32 v29, v174, v18, v215
	v_cvt_pk_bf16_f32 v29, v29, v29
	ds_write_b16 v210, v29 offset:61952
	v_fma_f32 v29, v172, v18, v215
	v_cvt_pk_bf16_f32 v29, v29, v29
	ds_write_b16 v211, v29 offset:62208
	v_fma_f32 v29, v167, v18, v215
	v_cvt_pk_bf16_f32 v29, v29, v29
	ds_write_b16 v212, v29 offset:62464
	v_fma_f32 v29, v165, v18, v215
	v_cvt_pk_bf16_f32 v29, v29, v29
	ds_write_b16 v213, v29 offset:62720
	v_fma_f32 v29, v64, v18, v215
	v_cvt_pk_bf16_f32 v29, v29, v29
	ds_write_b16 v214, v29 offset:62976
	v_fma_f32 v29, v62, v18, v215
	v_cvt_pk_bf16_f32 v29, v29, v29
	ds_write_b16 v35, v29 offset:63232
	v_fma_f32 v29, v170, v18, v215
	v_cvt_pk_bf16_f32 v29, v29, v29
	ds_write_b16 v200, v29 offset:63488
	v_fma_f32 v29, v166, v18, v215
	v_cvt_pk_bf16_f32 v29, v29, v29
	ds_write_b16 v201, v29 offset:63744
	v_fma_f32 v29, v65, v18, v215
	v_cvt_pk_bf16_f32 v29, v29, v29
	ds_write_b16 v202, v29 offset:64000
	v_fma_f32 v29, v63, v18, v215
	v_cvt_pk_bf16_f32 v29, v29, v29
	ds_write_b16 v203, v29 offset:64256
	v_fma_f32 v29, v60, v18, v215
	v_cvt_pk_bf16_f32 v29, v29, v29
	ds_write_b16 v204, v29 offset:64512
	v_fma_f32 v29, v59, v18, v215
	v_cvt_pk_bf16_f32 v29, v29, v29
	ds_write_b16 v205, v29 offset:64768
	v_fma_f32 v29, v57, v18, v215
	v_cvt_pk_bf16_f32 v29, v29, v29
	ds_write_b16 v206, v29 offset:65024
	v_fma_f32 v29, v55, v18, v215
	v_cvt_pk_bf16_f32 v29, v29, v29
	ds_write_b16 v207, v29 offset:65280
	v_fma_f32 v29, v61, v18, v215
	v_cvt_pk_bf16_f32 v29, v29, v29
	v_add3_u32 v35, v38, v194, v27
	ds_write_b16 v35, v29 offset:10240
	v_fma_f32 v29, v58, v18, v215
	v_cvt_pk_bf16_f32 v29, v29, v29
	v_add3_u32 v55, v38, v192, v27
	ds_write_b16 v55, v29 offset:10496
	v_fma_f32 v29, v56, v18, v215
	v_cvt_pk_bf16_f32 v29, v29, v29
	v_add3_u32 v56, v38, v190, v27
	ds_write_b16 v56, v29 offset:10752
	v_fma_f32 v29, v54, v18, v215
	v_cvt_pk_bf16_f32 v29, v29, v29
	v_add3_u32 v54, v38, v189, v27
	ds_write_b16 v54, v29 offset:11008
	v_fma_f32 v29, v53, v18, v215
	v_cvt_pk_bf16_f32 v29, v29, v29
	v_add3_u32 v53, v38, v188, v27
	ds_write_b16 v53, v29 offset:11264
	v_fma_f32 v29, v51, v18, v215
	v_cvt_pk_bf16_f32 v29, v29, v29
	v_add3_u32 v51, v38, v187, v27
	ds_write_b16 v51, v29 offset:11520
	v_fma_f32 v29, v49, v18, v215
	v_cvt_pk_bf16_f32 v29, v29, v29
	v_add3_u32 v49, v38, v184, v27
	ds_write_b16 v49, v29 offset:11776
	v_fma_f32 v29, v47, v18, v215
	v_cvt_pk_bf16_f32 v29, v29, v29
	v_add3_u32 v45, v38, v45, v27
	ds_write_b16 v45, v29 offset:12032
	v_fma_f32 v29, v52, v18, v215
	v_cvt_pk_bf16_f32 v29, v29, v29
	v_add3_u32 v46, v38, v46, v27
	ds_write_b16 v46, v29 offset:12288
	v_fma_f32 v29, v50, v18, v215
	v_cvt_pk_bf16_f32 v29, v29, v29
	v_add3_u32 v46, v38, v199, v27
	ds_write_b16 v46, v29 offset:12544
	v_fma_f32 v29, v48, v18, v215
	v_cvt_pk_bf16_f32 v29, v29, v29
	v_add3_u32 v46, v38, v198, v27
	ds_write_b16 v46, v29 offset:12800
	v_mul_f32_e32 v29, v37, v18
	v_bfe_u32 v36, v29, 16, 1
	v_add3_u32 v29, v29, v36, s15
	v_add3_u32 v36, v38, v197, v27
	ds_write_b16_d16_hi v36, v29 offset:13056
	v_fma_f32 v29, v34, v18, v215
	v_cvt_pk_bf16_f32 v29, v29, v29
	v_add3_u32 v34, v38, v196, v27
	ds_write_b16 v34, v29 offset:13312
	v_sub_f32_e32 v29, v24, v39
	v_pk_fma_f32 v[24:25], v[40:41], s[22:23], v[24:25] op_sel_hi:[1,0,1] neg_lo:[1,0,0] neg_hi:[1,0,0]
	v_mul_f32_e32 v29, v29, v18
	v_mul_f32_e32 v24, v25, v18
	v_bfe_u32 v34, v29, 16, 1
	v_bfe_u32 v25, v24, 16, 1
	v_add3_u32 v29, v29, v34, s15
	v_add3_u32 v34, v38, v195, v27
	v_add3_u32 v24, v24, v25, s15
	v_add3_u32 v25, v38, v193, v27
	ds_write_b16_d16_hi v34, v29 offset:13568
	ds_write_b16_d16_hi v25, v24 offset:13824
	v_pk_fma_f32 v[24:25], v[40:41], s[22:23], v[32:33] op_sel_hi:[1,0,1] neg_lo:[1,0,0] neg_hi:[1,0,0]
	v_and_b32_e32 v167, 15, v43
	v_mul_f32_e32 v24, v25, v18
	v_bfe_u32 v25, v24, 16, 1
	v_add3_u32 v24, v24, v25, s15
	v_add3_u32 v25, v38, v191, v27
	ds_write_b16_d16_hi v25, v24 offset:14080
	v_fma_f32 v24, v28, v18, v215
	v_cvt_pk_bf16_f32 v24, v24, v24
	ds_write_b16 v35, v24 offset:14336
	v_sub_f32_e32 v24, v22, v39
	v_pk_fma_f32 v[22:23], v[40:41], s[22:23], v[22:23] op_sel_hi:[1,0,1] neg_lo:[1,0,0] neg_hi:[1,0,0]
	v_mul_f32_e32 v24, v24, v18
	v_mul_f32_e32 v22, v23, v18
	v_bfe_u32 v25, v24, 16, 1
	v_bfe_u32 v23, v22, 16, 1
	v_add3_u32 v24, v24, v25, s15
	v_add3_u32 v22, v22, v23, s15
	ds_write_b16_d16_hi v55, v24 offset:14592
	ds_write_b16_d16_hi v56, v22 offset:14848
	v_pk_fma_f32 v[22:23], v[40:41], s[22:23], v[30:31] op_sel_hi:[1,0,1] neg_lo:[1,0,0] neg_hi:[1,0,0]
	s_nop 0
	v_mul_f32_e32 v22, v23, v18
	v_bfe_u32 v23, v22, 16, 1
	v_add3_u32 v22, v22, v23, s15
	ds_write_b16_d16_hi v54, v22 offset:15104
	v_fma_f32 v22, v26, v18, v215
	v_cvt_pk_bf16_f32 v22, v22, v22
	ds_write_b16 v53, v22 offset:15360
	v_sub_f32_e32 v22, v20, v39
	v_pk_fma_f32 v[20:21], v[40:41], s[22:23], v[20:21] op_sel_hi:[1,0,1] neg_lo:[1,0,0] neg_hi:[1,0,0]
	v_mul_f32_e32 v22, v22, v18
	v_mul_f32_e32 v20, v21, v18
	v_mul_f32_e32 v18, v19, v18
	v_bfe_u32 v23, v22, 16, 1
	v_bfe_u32 v21, v20, 16, 1
	v_bfe_u32 v19, v18, 16, 1
	v_add3_u32 v22, v22, v23, s15
	v_add3_u32 v20, v20, v21, s15
	v_add3_u32 v18, v18, v19, s15
	ds_write_b16_d16_hi v51, v22 offset:15616
	ds_write_b16_d16_hi v49, v20 offset:15872
	ds_write_b16_d16_hi v45, v18 offset:16128
	v_lshrrev_b32_e32 v18, 1, v43
	v_and_b32_e32 v18, 32, v18
	v_lshl_or_b32 v166, v44, 6, v18
	v_or_b32_e32 v18, v166, v168
	v_lshl_add_u32 v165, v18, 8, 32
	v_bitop3_b32 v18, v42, v167, 1 bitop3:0x6c
	v_lshl_add_u32 v18, v18, 4, v165
	s_waitcnt lgkmcnt(0)
	s_barrier
	ds_read_b128 v[170:173], v18 offset:55296
	s_waitcnt lgkmcnt(0)
	v_mfma_f32_32x32x16_bf16 v[50:65], v[170:173], v[2:5], 0
	v_mfma_f32_32x32x16_bf16 v[34:49], v[170:173], v[6:9], 0
	v_mfma_f32_32x32x16_bf16 v[18:33], v[170:173], v[10:13], 0
	v_mfma_f32_32x32x16_bf16 v[2:17], v[170:173], v[14:17], 0
	v_bitop3_b32 v170, v169, v167, 2 bitop3:0x36
	v_lshl_add_u32 v170, v170, 4, v165
	ds_read_b128 v[170:173], v170 offset:55296
	s_waitcnt lgkmcnt(0)
	v_mfma_f32_32x32x16_bf16 v[50:65], v[170:173], v[138:141], v[50:65]
	v_bitop3_b32 v138, v169, v167, 4 bitop3:0x36
	v_lshl_add_u32 v138, v138, 4, v165
	ds_read_b128 v[138:141], v138 offset:55296
	v_mfma_f32_32x32x16_bf16 v[34:49], v[170:173], v[142:145], v[34:49]
	v_mfma_f32_32x32x16_bf16 v[18:33], v[170:173], v[146:149], v[18:33]
	s_waitcnt lgkmcnt(0)
	v_mfma_f32_32x32x16_bf16 v[34:49], v[138:141], v[126:129], v[34:49]
	v_bitop3_b32 v126, v169, v167, 6 bitop3:0x36
	v_lshl_add_u32 v126, v126, 4, v165
	ds_read_b128 v[126:129], v126 offset:55296
	v_mfma_f32_32x32x16_bf16 v[2:17], v[170:173], v[150:153], v[2:17]
	v_mfma_f32_32x32x16_bf16 v[18:33], v[138:141], v[130:133], v[18:33]
	s_waitcnt lgkmcnt(0)
	v_mfma_f32_32x32x16_bf16 v[34:49], v[126:129], v[114:117], v[34:49]
	v_bitop3_b32 v114, v169, v167, 8 bitop3:0x36
	v_lshl_add_u32 v114, v114, 4, v165
	ds_read_b128 v[114:117], v114 offset:55296
	v_mfma_f32_32x32x16_bf16 v[2:17], v[138:141], v[134:137], v[2:17]
	v_mfma_f32_32x32x16_bf16 v[18:33], v[126:129], v[118:121], v[18:33]
	v_mfma_f32_32x32x16_bf16 v[2:17], v[126:129], v[122:125], v[2:17]
	v_lshlrev_b32_e32 v128, 7, v164
	v_or_b32_e32 v126, v128, v168
	v_ashrrev_i32_e32 v127, 31, v126
	v_lshlrev_b64 v[130:131], 2, v[126:127]
	v_lshl_or_b32 v122, v169, 2, v166
	v_or_b32_e32 v124, s3, v168
	v_mov_b32_e32 v125, s5
	s_waitcnt lgkmcnt(0)
	v_mfma_f32_32x32x16_bf16 v[18:33], v[114:117], v[106:109], v[18:33]
	v_bitop3_b32 v106, v169, v167, 10 bitop3:0x36
	v_lshl_add_u32 v106, v106, 4, v165
	ds_read_b128 v[106:109], v106 offset:55296
	v_lshl_add_u64 v[132:133], s[6:7], 0, v[130:131]
	v_lshl_add_u64 v[130:131], s[92:93], 0, v[130:131]
	v_ashrrev_i32_e32 v123, 31, v122
	v_lshlrev_b64 v[122:123], 1, v[122:123]
	v_mfma_f32_32x32x16_bf16 v[2:17], v[114:117], v[110:113], v[2:17]
	s_add_i32 s3, s3, s18
	s_cmpk_gt_i32 s4, 0x7f
	s_waitcnt lgkmcnt(0)
	v_mfma_f32_32x32x16_bf16 v[18:33], v[106:109], v[98:101], v[18:33]
	v_bitop3_b32 v98, v169, v167, 12 bitop3:0x36
	v_lshl_add_u32 v98, v98, 4, v165
	ds_read_b128 v[98:101], v98 offset:55296
	v_mfma_f32_32x32x16_bf16 v[2:17], v[106:109], v[102:105], v[2:17]
	s_waitcnt lgkmcnt(0)
	v_mfma_f32_32x32x16_bf16 v[2:17], v[98:101], v[94:97], v[2:17]
	v_bitop3_b32 v94, v169, v167, 14 bitop3:0x36
	v_lshl_add_u32 v94, v94, 4, v165
	ds_read_b128 v[94:97], v94 offset:55296
	v_ashrrev_i32_e32 v167, 31, v166
	s_waitcnt lgkmcnt(0)
	v_mfma_f32_32x32x16_bf16 v[2:17], v[94:97], v[90:93], v[2:17]
	v_lshlrev_b64 v[90:91], 2, v[166:167]
	v_lshl_add_u64 v[92:93], s[10:11], 0, v[90:91]
	v_lshl_add_u64 v[90:91], s[40:41], 0, v[90:91]
	v_lshl_add_u64 v[92:93], v[92:93], 0, v[154:155]
	v_lshl_add_u64 v[94:95], v[90:91], 0, v[154:155]
	global_load_dwordx4 v[114:117], v[92:93], off
	global_load_dwordx4 v[118:121], v[94:95], off
	global_load_dwordx4 v[106:109], v[92:93], off offset:32
	global_load_dwordx4 v[110:113], v[94:95], off offset:32
	global_load_dwordx4 v[98:101], v[92:93], off offset:64
	global_load_dwordx4 v[102:105], v[94:95], off offset:64
	s_nop 0
	global_load_dwordx4 v[90:93], v[92:93], off offset:96
	s_nop 0
	global_load_dwordx4 v[94:97], v[94:95], off offset:96
	s_nop 0
	global_load_dword v142, v[132:133], off
	global_load_dword v143, v[132:133], off offset:128
	global_load_dword v144, v[132:133], off offset:256
	global_load_dword v145, v[132:133], off offset:384
	global_load_dword v146, v[130:131], off
	global_load_dword v147, v[130:131], off offset:128
	global_load_dword v148, v[130:131], off offset:256
	global_load_dword v149, v[130:131], off offset:384
	v_lshlrev_b64 v[134:135], 11, v[124:125]
	v_lshl_add_u64 v[134:135], s[62:63], 0, v[134:135]
	v_lshl_add_u64 v[134:135], v[134:135], 0, v[122:123]
	v_add_co_u32_e32 v136, vcc, 0x10000, v134
	s_nop 1
	v_addc_co_u32_e32 v137, vcc, 0, v135, vcc
	v_add_co_u32_e32 v138, vcc, 0x20000, v134
	s_nop 1
	v_addc_co_u32_e32 v139, vcc, 0, v135, vcc
	v_add_co_u32_e32 v140, vcc, 0x30000, v134
	s_nop 1
	v_addc_co_u32_e32 v141, vcc, 0, v135, vcc
	s_barrier
	v_and_b32_e32 v150, 31, v0
	v_lshlrev_b32_e32 v170, 6, v150
	v_bfe_u32 v151, v0, 5, 1
	v_lshl_add_u32 v170, v151, 3, v170
	v_lshrrev_b32_e32 v168, 6, v0
	v_lshl_add_u32 v170, v168, 13, v170
	v_add_u32_e32 v170, 0xd820, v170
	v_bfe_u32 v150, v0, 1, 2
	v_xor_b32_e32 v151, 0, v150
	v_lshl_add_u32 v152, v151, 4, v170
	v_xor_b32_e32 v151, 1, v150
	v_lshl_add_u32 v153, v151, 4, v170
	v_xor_b32_e32 v151, 2, v150
	v_lshl_add_u32 v164, v151, 4, v170
	v_xor_b32_e32 v151, 3, v150
	v_lshl_add_u32 v165, v151, 4, v170
	v_bfe_u32 v169, v0, 2, 4
	v_lshlrev_b32_e32 v166, 6, v169
	v_and_b32_e32 v151, 3, v0
	v_bfe_u32 v150, v0, 3, 2
	v_xor_b32_e32 v150, v151, v150
	v_lshl_add_u32 v166, v150, 4, v166
	v_lshl_add_u32 v166, v168, 13, v166
	v_add_u32_e32 v166, 0xd820, v166
	v_and_b32_e32 v167, -32, v124
	v_add_u32_e32 v167, v167, v169
	v_lshlrev_b32_e32 v167, 11, v167
	v_lshl_add_u32 v167, v168, 6, v167
	v_lshl_add_u32 v167, v151, 4, v167
	s_waitcnt vmcnt(0)
	s_nop 1
	v_permlane32_swap_b32 v216, v218
	v_permlane32_swap_b32 v217, v219
	v_permlane32_swap_b32 v220, v222
	v_permlane32_swap_b32 v221, v223
	v_permlane32_swap_b32 v224, v226
	v_permlane32_swap_b32 v225, v227
	v_permlane32_swap_b32 v228, v230
	v_permlane32_swap_b32 v229, v231
	v_permlane32_swap_b32 v232, v234
	v_permlane32_swap_b32 v233, v235
	v_permlane32_swap_b32 v236, v238
	v_permlane32_swap_b32 v237, v239
	v_permlane32_swap_b32 v252, v254
	v_permlane32_swap_b32 v253, v255
	v_mul_f32_e32 v150, v118, v142
	v_fmac_f32_e32 v150, v50, v114
	v_add_f32_e32 v50, v146, v150
	v_lshlrev_b32_e32 v151, 16, v216
	v_mul_f32_e32 v50, v50, v151
	v_mul_f32_e32 v150, v119, v142
	v_fmac_f32_e32 v150, v51, v115
	v_add_f32_e32 v51, v146, v150
	v_and_b32_e32 v151, 0xffff0000, v216
	v_mul_f32_e32 v51, v51, v151
	v_mul_f32_e32 v150, v120, v142
	v_fmac_f32_e32 v150, v52, v116
	v_add_f32_e32 v52, v146, v150
	v_lshlrev_b32_e32 v151, 16, v217
	v_mul_f32_e32 v52, v52, v151
	v_mul_f32_e32 v150, v121, v142
	v_fmac_f32_e32 v150, v53, v117
	v_add_f32_e32 v53, v146, v150
	v_and_b32_e32 v151, 0xffff0000, v217
	v_mul_f32_e32 v53, v53, v151
	v_cvt_pk_bf16_f32 v50, v50, v51
	v_cvt_pk_bf16_f32 v51, v52, v53
	ds_write_b64 v152, v[50:51] offset:0
	v_mul_f32_e32 v150, v110, v142
	v_fmac_f32_e32 v150, v54, v106
	v_add_f32_e32 v54, v146, v150
	v_lshlrev_b32_e32 v151, 16, v218
	v_mul_f32_e32 v54, v54, v151
	v_mul_f32_e32 v150, v111, v142
	v_fmac_f32_e32 v150, v55, v107
	v_add_f32_e32 v55, v146, v150
	v_and_b32_e32 v151, 0xffff0000, v218
	v_mul_f32_e32 v55, v55, v151
	v_mul_f32_e32 v150, v112, v142
	v_fmac_f32_e32 v150, v56, v108
	v_add_f32_e32 v56, v146, v150
	v_lshlrev_b32_e32 v151, 16, v219
	v_mul_f32_e32 v56, v56, v151
	v_mul_f32_e32 v150, v113, v142
	v_fmac_f32_e32 v150, v57, v109
	v_add_f32_e32 v57, v146, v150
	v_and_b32_e32 v151, 0xffff0000, v219
	v_mul_f32_e32 v57, v57, v151
	v_cvt_pk_bf16_f32 v54, v54, v55
	v_cvt_pk_bf16_f32 v55, v56, v57
	ds_write_b64 v153, v[54:55] offset:0
	v_mul_f32_e32 v150, v102, v142
	v_fmac_f32_e32 v150, v58, v98
	v_add_f32_e32 v58, v146, v150
	v_lshlrev_b32_e32 v151, 16, v220
	v_mul_f32_e32 v58, v58, v151
	v_mul_f32_e32 v150, v103, v142
	v_fmac_f32_e32 v150, v59, v99
	v_add_f32_e32 v59, v146, v150
	v_and_b32_e32 v151, 0xffff0000, v220
	v_mul_f32_e32 v59, v59, v151
	v_mul_f32_e32 v150, v104, v142
	v_fmac_f32_e32 v150, v60, v100
	v_add_f32_e32 v60, v146, v150
	v_lshlrev_b32_e32 v151, 16, v221
	v_mul_f32_e32 v60, v60, v151
	v_mul_f32_e32 v150, v105, v142
	v_fmac_f32_e32 v150, v61, v101
	v_add_f32_e32 v61, v146, v150
	v_and_b32_e32 v151, 0xffff0000, v221
	v_mul_f32_e32 v61, v61, v151
	v_cvt_pk_bf16_f32 v58, v58, v59
	v_cvt_pk_bf16_f32 v59, v60, v61
	ds_write_b64 v164, v[58:59] offset:0
	v_mul_f32_e32 v150, v94, v142
	v_fmac_f32_e32 v150, v62, v90
	v_add_f32_e32 v62, v146, v150
	v_lshlrev_b32_e32 v151, 16, v222
	v_mul_f32_e32 v62, v62, v151
	v_mul_f32_e32 v150, v95, v142
	v_fmac_f32_e32 v150, v63, v91
	v_add_f32_e32 v63, v146, v150
	v_and_b32_e32 v151, 0xffff0000, v222
	v_mul_f32_e32 v63, v63, v151
	v_mul_f32_e32 v150, v96, v142
	v_fmac_f32_e32 v150, v64, v92
	v_add_f32_e32 v64, v146, v150
	v_lshlrev_b32_e32 v151, 16, v223
	v_mul_f32_e32 v64, v64, v151
	v_mul_f32_e32 v150, v97, v142
	v_fmac_f32_e32 v150, v65, v93
	v_add_f32_e32 v65, v146, v150
	v_and_b32_e32 v151, 0xffff0000, v223
	v_mul_f32_e32 v65, v65, v151
	v_cvt_pk_bf16_f32 v62, v62, v63
	v_cvt_pk_bf16_f32 v63, v64, v65
	ds_write_b64 v165, v[62:63] offset:0
	v_mul_f32_e32 v150, v118, v143
	v_fmac_f32_e32 v150, v34, v114
	v_add_f32_e32 v34, v147, v150
	v_lshlrev_b32_e32 v151, 16, v224
	v_mul_f32_e32 v34, v34, v151
	v_mul_f32_e32 v150, v119, v143
	v_fmac_f32_e32 v150, v35, v115
	v_add_f32_e32 v35, v147, v150
	v_and_b32_e32 v151, 0xffff0000, v224
	v_mul_f32_e32 v35, v35, v151
	v_mul_f32_e32 v150, v120, v143
	v_fmac_f32_e32 v150, v36, v116
	v_add_f32_e32 v36, v147, v150
	v_lshlrev_b32_e32 v151, 16, v225
	v_mul_f32_e32 v36, v36, v151
	v_mul_f32_e32 v150, v121, v143
	v_fmac_f32_e32 v150, v37, v117
	v_add_f32_e32 v37, v147, v150
	v_and_b32_e32 v151, 0xffff0000, v225
	v_mul_f32_e32 v37, v37, v151
	v_cvt_pk_bf16_f32 v34, v34, v35
	v_cvt_pk_bf16_f32 v35, v36, v37
	ds_write_b64 v152, v[34:35] offset:2048
	v_mul_f32_e32 v150, v110, v143
	v_fmac_f32_e32 v150, v38, v106
	v_add_f32_e32 v38, v147, v150
	v_lshlrev_b32_e32 v151, 16, v226
	v_mul_f32_e32 v38, v38, v151
	v_mul_f32_e32 v150, v111, v143
	v_fmac_f32_e32 v150, v39, v107
	v_add_f32_e32 v39, v147, v150
	v_and_b32_e32 v151, 0xffff0000, v226
	v_mul_f32_e32 v39, v39, v151
	v_mul_f32_e32 v150, v112, v143
	v_fmac_f32_e32 v150, v40, v108
	v_add_f32_e32 v40, v147, v150
	v_lshlrev_b32_e32 v151, 16, v227
	v_mul_f32_e32 v40, v40, v151
	v_mul_f32_e32 v150, v113, v143
	v_fmac_f32_e32 v150, v41, v109
	v_add_f32_e32 v41, v147, v150
	v_and_b32_e32 v151, 0xffff0000, v227
	v_mul_f32_e32 v41, v41, v151
	v_cvt_pk_bf16_f32 v38, v38, v39
	v_cvt_pk_bf16_f32 v39, v40, v41
	ds_write_b64 v153, v[38:39] offset:2048
	v_mul_f32_e32 v150, v102, v143
	v_fmac_f32_e32 v150, v42, v98
	v_add_f32_e32 v42, v147, v150
	v_lshlrev_b32_e32 v151, 16, v228
	v_mul_f32_e32 v42, v42, v151
	v_mul_f32_e32 v150, v103, v143
	v_fmac_f32_e32 v150, v43, v99
	v_add_f32_e32 v43, v147, v150
	v_and_b32_e32 v151, 0xffff0000, v228
	v_mul_f32_e32 v43, v43, v151
	v_mul_f32_e32 v150, v104, v143
	v_fmac_f32_e32 v150, v44, v100
	v_add_f32_e32 v44, v147, v150
	v_lshlrev_b32_e32 v151, 16, v229
	v_mul_f32_e32 v44, v44, v151
	v_mul_f32_e32 v150, v105, v143
	v_fmac_f32_e32 v150, v45, v101
	v_add_f32_e32 v45, v147, v150
	v_and_b32_e32 v151, 0xffff0000, v229
	v_mul_f32_e32 v45, v45, v151
	v_cvt_pk_bf16_f32 v42, v42, v43
	v_cvt_pk_bf16_f32 v43, v44, v45
	ds_write_b64 v164, v[42:43] offset:2048
	v_mul_f32_e32 v150, v94, v143
	v_fmac_f32_e32 v150, v46, v90
	v_add_f32_e32 v46, v147, v150
	v_lshlrev_b32_e32 v151, 16, v230
	v_mul_f32_e32 v46, v46, v151
	v_mul_f32_e32 v150, v95, v143
	v_fmac_f32_e32 v150, v47, v91
	v_add_f32_e32 v47, v147, v150
	v_and_b32_e32 v151, 0xffff0000, v230
	v_mul_f32_e32 v47, v47, v151
	v_mul_f32_e32 v150, v96, v143
	v_fmac_f32_e32 v150, v48, v92
	v_add_f32_e32 v48, v147, v150
	v_lshlrev_b32_e32 v151, 16, v231
	v_mul_f32_e32 v48, v48, v151
	v_mul_f32_e32 v150, v97, v143
	v_fmac_f32_e32 v150, v49, v93
	v_add_f32_e32 v49, v147, v150
	v_and_b32_e32 v151, 0xffff0000, v231
	v_mul_f32_e32 v49, v49, v151
	v_cvt_pk_bf16_f32 v46, v46, v47
	v_cvt_pk_bf16_f32 v47, v48, v49
	ds_write_b64 v165, v[46:47] offset:2048
	v_mul_f32_e32 v150, v118, v144
	v_fmac_f32_e32 v150, v18, v114
	v_add_f32_e32 v18, v148, v150
	v_lshlrev_b32_e32 v151, 16, v232
	v_mul_f32_e32 v18, v18, v151
	v_mul_f32_e32 v150, v119, v144
	v_fmac_f32_e32 v150, v19, v115
	v_add_f32_e32 v19, v148, v150
	v_and_b32_e32 v151, 0xffff0000, v232
	v_mul_f32_e32 v19, v19, v151
	v_mul_f32_e32 v150, v120, v144
	v_fmac_f32_e32 v150, v20, v116
	v_add_f32_e32 v20, v148, v150
	v_lshlrev_b32_e32 v151, 16, v233
	v_mul_f32_e32 v20, v20, v151
	v_mul_f32_e32 v150, v121, v144
	v_fmac_f32_e32 v150, v21, v117
	v_add_f32_e32 v21, v148, v150
	v_and_b32_e32 v151, 0xffff0000, v233
	v_mul_f32_e32 v21, v21, v151
	v_cvt_pk_bf16_f32 v18, v18, v19
	v_cvt_pk_bf16_f32 v19, v20, v21
	ds_write_b64 v152, v[18:19] offset:4096
	v_mul_f32_e32 v150, v110, v144
	v_fmac_f32_e32 v150, v22, v106
	v_add_f32_e32 v22, v148, v150
	v_lshlrev_b32_e32 v151, 16, v234
	v_mul_f32_e32 v22, v22, v151
	v_mul_f32_e32 v150, v111, v144
	v_fmac_f32_e32 v150, v23, v107
	v_add_f32_e32 v23, v148, v150
	v_and_b32_e32 v151, 0xffff0000, v234
	v_mul_f32_e32 v23, v23, v151
	v_mul_f32_e32 v150, v112, v144
	v_fmac_f32_e32 v150, v24, v108
	v_add_f32_e32 v24, v148, v150
	v_lshlrev_b32_e32 v151, 16, v235
	v_mul_f32_e32 v24, v24, v151
	v_mul_f32_e32 v150, v113, v144
	v_fmac_f32_e32 v150, v25, v109
	v_add_f32_e32 v25, v148, v150
	v_and_b32_e32 v151, 0xffff0000, v235
	v_mul_f32_e32 v25, v25, v151
	v_cvt_pk_bf16_f32 v22, v22, v23
	v_cvt_pk_bf16_f32 v23, v24, v25
	ds_write_b64 v153, v[22:23] offset:4096
	v_mul_f32_e32 v150, v102, v144
	v_fmac_f32_e32 v150, v26, v98
	v_add_f32_e32 v26, v148, v150
	v_lshlrev_b32_e32 v151, 16, v236
	v_mul_f32_e32 v26, v26, v151
	v_mul_f32_e32 v150, v103, v144
	v_fmac_f32_e32 v150, v27, v99
	v_add_f32_e32 v27, v148, v150
	v_and_b32_e32 v151, 0xffff0000, v236
	v_mul_f32_e32 v27, v27, v151
	v_mul_f32_e32 v150, v104, v144
	v_fmac_f32_e32 v150, v28, v100
	v_add_f32_e32 v28, v148, v150
	v_lshlrev_b32_e32 v151, 16, v237
	v_mul_f32_e32 v28, v28, v151
	v_mul_f32_e32 v150, v105, v144
	v_fmac_f32_e32 v150, v29, v101
	v_add_f32_e32 v29, v148, v150
	v_and_b32_e32 v151, 0xffff0000, v237
	v_mul_f32_e32 v29, v29, v151
	v_cvt_pk_bf16_f32 v26, v26, v27
	v_cvt_pk_bf16_f32 v27, v28, v29
	ds_write_b64 v164, v[26:27] offset:4096
	v_mul_f32_e32 v150, v94, v144
	v_fmac_f32_e32 v150, v30, v90
	v_add_f32_e32 v30, v148, v150
	v_lshlrev_b32_e32 v151, 16, v238
	v_mul_f32_e32 v30, v30, v151
	v_mul_f32_e32 v150, v95, v144
	v_fmac_f32_e32 v150, v31, v91
	v_add_f32_e32 v31, v148, v150
	v_and_b32_e32 v151, 0xffff0000, v238
	v_mul_f32_e32 v31, v31, v151
	v_mul_f32_e32 v150, v96, v144
	v_fmac_f32_e32 v150, v32, v92
	v_add_f32_e32 v32, v148, v150
	v_lshlrev_b32_e32 v151, 16, v239
	v_mul_f32_e32 v32, v32, v151
	v_mul_f32_e32 v150, v97, v144
	v_fmac_f32_e32 v150, v33, v93
	v_add_f32_e32 v33, v148, v150
	v_and_b32_e32 v151, 0xffff0000, v239
	v_mul_f32_e32 v33, v33, v151
	v_cvt_pk_bf16_f32 v30, v30, v31
	v_cvt_pk_bf16_f32 v31, v32, v33
	ds_write_b64 v165, v[30:31] offset:4096
	v_mul_f32_e32 v150, v118, v145
	v_fmac_f32_e32 v150, v2, v114
	v_add_f32_e32 v2, v149, v150
	v_lshlrev_b32_e32 v151, 16, v252
	v_mul_f32_e32 v2, v2, v151
	v_mul_f32_e32 v150, v119, v145
	v_fmac_f32_e32 v150, v3, v115
	v_add_f32_e32 v3, v149, v150
	v_and_b32_e32 v151, 0xffff0000, v252
	v_mul_f32_e32 v3, v3, v151
	v_mul_f32_e32 v150, v120, v145
	v_fmac_f32_e32 v150, v4, v116
	v_add_f32_e32 v4, v149, v150
	v_lshlrev_b32_e32 v151, 16, v253
	v_mul_f32_e32 v4, v4, v151
	v_mul_f32_e32 v150, v121, v145
	v_fmac_f32_e32 v150, v5, v117
	v_add_f32_e32 v5, v149, v150
	v_and_b32_e32 v151, 0xffff0000, v253
	v_mul_f32_e32 v5, v5, v151
	v_cvt_pk_bf16_f32 v2, v2, v3
	v_cvt_pk_bf16_f32 v3, v4, v5
	ds_write_b64 v152, v[2:3] offset:6144
	v_mul_f32_e32 v150, v110, v145
	v_fmac_f32_e32 v150, v6, v106
	v_add_f32_e32 v6, v149, v150
	v_lshlrev_b32_e32 v151, 16, v254
	v_mul_f32_e32 v6, v6, v151
	v_mul_f32_e32 v150, v111, v145
	v_fmac_f32_e32 v150, v7, v107
	v_add_f32_e32 v7, v149, v150
	v_and_b32_e32 v151, 0xffff0000, v254
	v_mul_f32_e32 v7, v7, v151
	v_mul_f32_e32 v150, v112, v145
	v_fmac_f32_e32 v150, v8, v108
	v_add_f32_e32 v8, v149, v150
	v_lshlrev_b32_e32 v151, 16, v255
	v_mul_f32_e32 v8, v8, v151
	v_mul_f32_e32 v150, v113, v145
	v_fmac_f32_e32 v150, v9, v109
	v_add_f32_e32 v9, v149, v150
	v_and_b32_e32 v151, 0xffff0000, v255
	v_mul_f32_e32 v9, v9, v151
	v_cvt_pk_bf16_f32 v6, v6, v7
	v_cvt_pk_bf16_f32 v7, v8, v9
	ds_write_b64 v153, v[6:7] offset:6144
	v_mul_f32_e32 v150, v102, v145
	v_fmac_f32_e32 v150, v10, v98
	v_add_f32_e32 v10, v149, v150
	v_lshlrev_b32_e32 v151, 16, v240
	v_mul_f32_e32 v10, v10, v151
	v_mul_f32_e32 v150, v103, v145
	v_fmac_f32_e32 v150, v11, v99
	v_add_f32_e32 v11, v149, v150
	v_and_b32_e32 v151, 0xffff0000, v240
	v_mul_f32_e32 v11, v11, v151
	v_mul_f32_e32 v150, v104, v145
	v_fmac_f32_e32 v150, v12, v100
	v_add_f32_e32 v12, v149, v150
	v_lshlrev_b32_e32 v151, 16, v241
	v_mul_f32_e32 v12, v12, v151
	v_mul_f32_e32 v150, v105, v145
	v_fmac_f32_e32 v150, v13, v101
	v_add_f32_e32 v13, v149, v150
	v_and_b32_e32 v151, 0xffff0000, v241
	v_mul_f32_e32 v13, v13, v151
	v_cvt_pk_bf16_f32 v10, v10, v11
	v_cvt_pk_bf16_f32 v11, v12, v13
	ds_write_b64 v164, v[10:11] offset:6144
	v_mul_f32_e32 v150, v94, v145
	v_fmac_f32_e32 v150, v14, v90
	v_add_f32_e32 v14, v149, v150
	v_lshlrev_b32_e32 v151, 16, v246
	v_mul_f32_e32 v14, v14, v151
	v_mul_f32_e32 v150, v95, v145
	v_fmac_f32_e32 v150, v15, v91
	v_add_f32_e32 v15, v149, v150
	v_and_b32_e32 v151, 0xffff0000, v246
	v_mul_f32_e32 v15, v15, v151
	v_mul_f32_e32 v150, v96, v145
	v_fmac_f32_e32 v150, v16, v92
	v_add_f32_e32 v16, v149, v150
	v_lshlrev_b32_e32 v151, 16, v247
	v_mul_f32_e32 v16, v16, v151
	v_mul_f32_e32 v150, v97, v145
	v_fmac_f32_e32 v150, v17, v93
	v_add_f32_e32 v17, v149, v150
	v_and_b32_e32 v151, 0xffff0000, v247
	v_mul_f32_e32 v17, v17, v151
	v_cvt_pk_bf16_f32 v14, v14, v15
	v_cvt_pk_bf16_f32 v15, v16, v17
	ds_write_b64 v165, v[14:15] offset:6144
	s_waitcnt lgkmcnt(0)
	ds_read_b128 v[2:5], v166 offset:0
	ds_read_b128 v[6:9], v166 offset:1024
	ds_read_b128 v[10:13], v166 offset:2048
	ds_read_b128 v[14:17], v166 offset:3072
	ds_read_b128 v[18:21], v166 offset:4096
	ds_read_b128 v[22:25], v166 offset:5120
	ds_read_b128 v[26:29], v166 offset:6144
	ds_read_b128 v[30:33], v166 offset:7168
	s_waitcnt lgkmcnt(7)
	global_store_dwordx4 v167, v[2:5], s[62:63] offset:1536
	v_add_u32_e32 v151, 0x8000, v167
	s_waitcnt lgkmcnt(6)
	global_store_dwordx4 v151, v[6:9], s[62:63] offset:1536
	v_add_u32_e32 v150, 0x10000, v167
	s_waitcnt lgkmcnt(5)
	global_store_dwordx4 v150, v[10:13], s[62:63] offset:1536
	v_add_u32_e32 v151, 0x18000, v167
	s_waitcnt lgkmcnt(4)
	global_store_dwordx4 v151, v[14:17], s[62:63] offset:1536
	v_add_u32_e32 v150, 0x20000, v167
	s_waitcnt lgkmcnt(3)
	global_store_dwordx4 v150, v[18:21], s[62:63] offset:1536
	v_add_u32_e32 v151, 0x28000, v167
	s_waitcnt lgkmcnt(2)
	global_store_dwordx4 v151, v[22:25], s[62:63] offset:1536
	v_add_u32_e32 v150, 0x30000, v167
	s_waitcnt lgkmcnt(1)
	global_store_dwordx4 v150, v[26:29], s[62:63] offset:1536
	v_add_u32_e32 v151, 0x38000, v167
	s_waitcnt lgkmcnt(0)
	global_store_dwordx4 v151, v[30:33], s[62:63] offset:1536
	s_barrier
	s_cbranch_scc0 .LBB0_779

.LBB0_849:
	v_mov_b32_e32 v43, v0
	s_ashr_i32 s5, s3, 31
	v_ashrrev_i32_e32 v44, 7, v43
	s_waitcnt vmcnt(7)
	v_add_u32_e32 v130, s2, v44
	v_ashrrev_i32_e32 v131, 31, v130
	v_and_b32_e32 v134, 31, v43
	s_waitcnt vmcnt(0)
	v_lshlrev_b64 v[2:3], 15, v[130:131]
	v_bfe_u32 v135, v43, 5, 1
	v_lshl_add_u64 v[2:3], s[56:57], 0, v[2:3]
	v_lshlrev_b32_e32 v154, 8, v134
	v_lshl_add_u64 v[2:3], v[2:3], 0, v[154:155]
	v_lshlrev_b32_e32 v154, 4, v135
	v_lshl_add_u64 v[18:19], v[2:3], 0, v[154:155]
	v_add_co_u32_e32 v20, vcc, s14, v18
	v_ashrrev_i32_e32 v45, 2, v43
	s_nop 0
	v_addc_co_u32_e32 v21, vcc, 0, v19, vcc
	v_add_co_u32_e32 v22, vcc, s17, v18
	global_load_dwordx4 v[2:5], v[18:19], off
	global_load_dwordx4 v[6:9], v[20:21], off
	v_addc_co_u32_e32 v23, vcc, 0, v19, vcc
	v_add_co_u32_e32 v24, vcc, s30, v18
	global_load_dwordx4 v[10:13], v[22:23], off
	s_nop 0
	v_addc_co_u32_e32 v25, vcc, 0, v19, vcc
	global_load_dwordx4 v[14:17], v[24:25], off
	global_load_dwordx4 v[114:117], v[18:19], off offset:32
	global_load_dwordx4 v[118:121], v[20:21], off offset:32
	global_load_dwordx4 v[122:125], v[22:23], off offset:32
	global_load_dwordx4 v[126:129], v[24:25], off offset:32
	global_load_dwordx4 v[102:105], v[20:21], off offset:64
	global_load_dwordx4 v[106:109], v[22:23], off offset:64
	global_load_dwordx4 v[110:113], v[24:25], off offset:64
	global_load_dwordx4 v[90:93], v[20:21], off offset:96
	global_load_dwordx4 v[94:97], v[22:23], off offset:96
	global_load_dwordx4 v[98:101], v[24:25], off offset:96
	global_load_dwordx4 v[82:85], v[22:23], off offset:128
	global_load_dwordx4 v[86:89], v[24:25], off offset:128
	global_load_dwordx4 v[74:77], v[22:23], off offset:160
	global_load_dwordx4 v[78:81], v[24:25], off offset:160
	global_load_dwordx4 v[70:73], v[24:25], off offset:192
	global_load_dwordx4 v[66:69], v[24:25], off offset:224
	v_add_u32_e32 v18, s3, v45
	v_ashrrev_i32_e32 v19, 31, v18
	v_lshlrev_b32_e32 v20, 6, v43
	v_lshlrev_b64 v[18:19], 12, v[18:19]
	v_and_b32_e32 v46, 0xc0, v20
	v_lshl_add_u64 v[18:19], s[60:61], 0, v[18:19]
	v_lshlrev_b32_e32 v20, 1, v46
	v_mov_b32_e32 v21, v155
	v_lshl_add_u64 v[34:35], v[18:19], 0, v[20:21]
	global_load_dwordx4 v[18:21], v[34:35], off offset:3632
	global_load_dwordx4 v[22:25], v[34:35], off offset:3616
	global_load_dwordx4 v[26:29], v[34:35], off offset:3600
	global_load_dwordx4 v[30:33], v[34:35], off offset:3584
	global_load_dwordx4 v[36:39], v[34:35], off offset:3680
	global_load_dwordx4 v[176:179], v[34:35], off offset:3664
	global_load_dwordx4 v[48:51], v[34:35], off offset:3648
	global_load_dwordx4 v[182:185], v[34:35], off offset:3696
	v_and_b32_e32 v215, 31, v0
	v_add_u32_e32 v215, s3, v215
	v_lshlrev_b32_e32 v215, 12, v215
	v_and_b32_e32 v245, 0x1c0, v0
	v_add_u32_e32 v215, v215, v245
	v_bfe_u32 v245, v0, 5, 1
	v_lshl_add_u32 v245, v245, 3, v215
	v_bfe_u32 v215, v0, 5, 1
	v_lshl_add_u32 v215, v215, 3, v245
	global_load_dwordx4 v[216:219], v215, s[60:61] offset:3072
	global_load_dwordx4 v[220:223], v215, s[60:61] offset:3104
	s_add_u32 s98, s60, 0x20000
	s_addc_u32 s99, s61, 0
	global_load_dwordx4 v[224:227], v215, s[98:99] offset:3072
	global_load_dwordx4 v[228:231], v215, s[98:99] offset:3104
	s_add_u32 s100, s60, 0x40000
	s_addc_u32 s101, s61, 0
	global_load_dwordx4 v[232:235], v215, s[100:101] offset:3072
	global_load_dwordx4 v[236:239], v215, s[100:101] offset:3104
	s_add_u32 s98, s60, 0x60000
	s_addc_u32 s99, s61, 0
	global_load_dwordx4 v[252:255], v215, s[98:99] offset:3072
	global_load_dwordx2 v[240:241], v245, s[98:99] offset:3104
	global_load_dwordx2 v[246:247], v245, s[98:99] offset:3120
	v_lshrrev_b32_e32 v42, 5, v43
	s_add_i32 s4, s4, s46
	s_waitcnt vmcnt(16)
	v_lshlrev_b32_e32 v144, 16, v18
	s_waitcnt vmcnt(15)
	v_lshlrev_b32_e32 v150, 16, v22
	s_waitcnt vmcnt(14)
	v_lshlrev_b32_e32 v168, 16, v26
	s_waitcnt vmcnt(13)
	v_lshlrev_b32_e32 v174, 16, v30
	v_and_b32_e32 v173, 0xffff0000, v30
	v_add_f32_e32 v30, 0, v174
	v_lshlrev_b32_e32 v172, 16, v31
	v_add_f32_e32 v30, v30, v173
	v_and_b32_e32 v171, 0xffff0000, v31
	v_mul_f32_e32 v31, v173, v173
	v_add_f32_e32 v30, v30, v172
	v_lshlrev_b32_e32 v170, 16, v32
	v_fmac_f32_e32 v31, v174, v174
	v_add_f32_e32 v30, v30, v171
	v_and_b32_e32 v169, 0xffff0000, v32
	v_fmac_f32_e32 v31, v172, v172
	v_add_f32_e32 v30, v30, v170
	v_lshlrev_b32_e32 v167, 16, v33
	v_fmac_f32_e32 v31, v171, v171
	v_add_f32_e32 v30, v30, v169
	v_and_b32_e32 v165, 0xffff0000, v33
	v_fmac_f32_e32 v31, v170, v170
	v_add_f32_e32 v30, v30, v167
	v_fmac_f32_e32 v31, v169, v169
	v_add_f32_e32 v30, v30, v165
	v_fmac_f32_e32 v31, v167, v167
	v_and_b32_e32 v166, 0xffff0000, v26
	v_add_f32_e32 v26, v30, v168
	v_fmac_f32_e32 v31, v165, v165
	v_lshlrev_b32_e32 v164, 16, v27
	v_add_f32_e32 v26, v26, v166
	v_and_b32_e32 v153, 0xffff0000, v27
	v_fmac_f32_e32 v31, v168, v168
	v_add_f32_e32 v26, v26, v164
	v_lshlrev_b32_e32 v152, 16, v28
	v_fmac_f32_e32 v31, v166, v166
	v_add_f32_e32 v26, v26, v153
	v_and_b32_e32 v151, 0xffff0000, v28
	v_fmac_f32_e32 v31, v164, v164
	v_add_f32_e32 v26, v26, v152
	v_lshlrev_b32_e32 v148, 16, v29
	v_fmac_f32_e32 v31, v153, v153
	v_add_f32_e32 v26, v26, v151
	v_and_b32_e32 v146, 0xffff0000, v29
	v_fmac_f32_e32 v31, v152, v152
	v_add_f32_e32 v26, v26, v148
	v_fmac_f32_e32 v31, v151, v151
	v_add_f32_e32 v26, v26, v146
	v_fmac_f32_e32 v31, v148, v148
	v_and_b32_e32 v149, 0xffff0000, v22
	v_add_f32_e32 v22, v26, v150
	v_fmac_f32_e32 v31, v146, v146
	v_lshlrev_b32_e32 v147, 16, v23
	v_add_f32_e32 v22, v22, v149
	v_and_b32_e32 v145, 0xffff0000, v23
	v_fmac_f32_e32 v31, v150, v150
	v_add_f32_e32 v22, v22, v147
	v_lshlrev_b32_e32 v143, 16, v24
	v_fmac_f32_e32 v31, v149, v149
	v_add_f32_e32 v22, v22, v145
	v_and_b32_e32 v141, 0xffff0000, v24
	v_fmac_f32_e32 v31, v147, v147
	v_add_f32_e32 v22, v22, v143
	v_lshlrev_b32_e32 v139, 16, v25
	v_fmac_f32_e32 v31, v145, v145
	v_add_f32_e32 v22, v22, v141
	v_and_b32_e32 v137, 0xffff0000, v25
	v_fmac_f32_e32 v31, v143, v143
	v_add_f32_e32 v22, v22, v139
	v_fmac_f32_e32 v31, v141, v141
	v_add_f32_e32 v22, v22, v137
	v_fmac_f32_e32 v31, v139, v139
	v_and_b32_e32 v142, 0xffff0000, v18
	v_add_f32_e32 v18, v22, v144
	v_fmac_f32_e32 v31, v137, v137
	v_lshlrev_b32_e32 v140, 16, v19
	v_add_f32_e32 v18, v18, v142
	v_and_b32_e32 v138, 0xffff0000, v19
	v_fmac_f32_e32 v31, v144, v144
	v_add_f32_e32 v18, v18, v140
	v_lshlrev_b32_e32 v133, 16, v20
	v_fmac_f32_e32 v31, v142, v142
	v_add_f32_e32 v18, v18, v138
	v_and_b32_e32 v131, 0xffff0000, v20
	v_fmac_f32_e32 v31, v140, v140
	v_add_f32_e32 v18, v18, v133
	v_lshlrev_b32_e32 v64, 16, v21
	v_fmac_f32_e32 v31, v138, v138
	v_add_f32_e32 v18, v18, v131
	v_and_b32_e32 v62, 0xffff0000, v21
	v_fmac_f32_e32 v31, v133, v133
	v_add_f32_e32 v18, v18, v64
	v_fmac_f32_e32 v31, v131, v131
	v_add_f32_e32 v18, v18, v62
	s_waitcnt vmcnt(10)
	v_lshlrev_b32_e32 v136, 16, v48
	v_fmac_f32_e32 v31, v64, v64
	v_and_b32_e32 v132, 0xffff0000, v48
	v_add_f32_e32 v18, v18, v136
	v_fmac_f32_e32 v31, v62, v62
	v_lshlrev_b32_e32 v65, 16, v49
	v_add_f32_e32 v18, v18, v132
	v_and_b32_e32 v63, 0xffff0000, v49
	v_fmac_f32_e32 v31, v136, v136
	v_add_f32_e32 v18, v18, v65
	v_lshlrev_b32_e32 v60, 16, v50
	v_fmac_f32_e32 v31, v132, v132
	v_add_f32_e32 v18, v18, v63
	v_and_b32_e32 v59, 0xffff0000, v50
	v_fmac_f32_e32 v31, v65, v65
	v_add_f32_e32 v18, v18, v60
	v_lshlrev_b32_e32 v57, 16, v51
	v_fmac_f32_e32 v31, v63, v63
	v_add_f32_e32 v18, v18, v59
	v_and_b32_e32 v55, 0xffff0000, v51
	v_fmac_f32_e32 v31, v60, v60
	v_add_f32_e32 v18, v18, v57
	v_fmac_f32_e32 v31, v59, v59
	v_add_f32_e32 v18, v18, v55
	v_lshlrev_b32_e32 v61, 16, v176
	v_fmac_f32_e32 v31, v57, v57
	v_and_b32_e32 v58, 0xffff0000, v176
	v_add_f32_e32 v18, v18, v61
	v_fmac_f32_e32 v31, v55, v55
	v_lshlrev_b32_e32 v56, 16, v177
	v_add_f32_e32 v18, v18, v58
	v_and_b32_e32 v54, 0xffff0000, v177
	v_fmac_f32_e32 v31, v61, v61
	v_add_f32_e32 v18, v18, v56
	v_lshlrev_b32_e32 v53, 16, v178
	v_fmac_f32_e32 v31, v58, v58
	v_add_f32_e32 v18, v18, v54
	v_and_b32_e32 v51, 0xffff0000, v178
	v_fmac_f32_e32 v31, v56, v56
	v_add_f32_e32 v18, v18, v53
	v_lshlrev_b32_e32 v49, 16, v179
	v_fmac_f32_e32 v31, v54, v54
	v_add_f32_e32 v18, v18, v51
	v_and_b32_e32 v47, 0xffff0000, v179
	v_fmac_f32_e32 v31, v53, v53
	v_add_f32_e32 v18, v18, v49
	v_fmac_f32_e32 v31, v51, v51
	v_add_f32_e32 v18, v18, v47
	v_lshlrev_b32_e32 v52, 16, v36
	v_fmac_f32_e32 v31, v49, v49
	v_and_b32_e32 v50, 0xffff0000, v36
	v_add_f32_e32 v18, v18, v52
	v_fmac_f32_e32 v31, v47, v47
	v_lshlrev_b32_e32 v48, 16, v37
	v_add_f32_e32 v18, v18, v50
	v_fmac_f32_e32 v31, v52, v52
	v_add_f32_e32 v18, v18, v48
	v_and_b32_e32 v37, 0xffff0000, v37
	v_fmac_f32_e32 v31, v50, v50
	v_lshlrev_b32_e32 v34, 16, v38
	v_mov_b32_e32 v35, v37
	v_add_f32_e32 v20, v18, v37
	v_fmac_f32_e32 v31, v48, v48
	v_and_b32_e32 v24, 0xffff0000, v38
	v_pk_mul_f32 v[18:19], v[34:35], v[34:35]
	v_add_f32_e32 v20, v20, v34
	v_lshlrev_b32_e32 v25, 16, v39
	v_add_f32_e32 v19, v19, v31
	v_add_f32_e32 v20, v20, v24
	v_add_f32_e32 v21, v18, v19
	v_pk_mul_f32 v[18:19], v[24:25], v[24:25]
	v_add_f32_e32 v20, v20, v25
	v_and_b32_e32 v33, 0xffff0000, v39
	v_add_f32_e32 v18, v18, v21
	s_waitcnt vmcnt(9)
	v_lshlrev_b32_e32 v28, 16, v182
	v_mov_b32_e32 v29, v33
	v_add_f32_e32 v20, v20, v33
	v_add_f32_e32 v21, v19, v18
	v_and_b32_e32 v22, 0xffff0000, v182
	v_pk_mul_f32 v[18:19], v[28:29], v[28:29]
	v_add_f32_e32 v20, v20, v28
	v_lshlrev_b32_e32 v23, 16, v183
	v_add_f32_e32 v19, v19, v21
	v_add_f32_e32 v20, v20, v22
	v_add_f32_e32 v21, v18, v19
	v_pk_mul_f32 v[18:19], v[22:23], v[22:23]
	v_add_f32_e32 v29, v20, v23
	v_and_b32_e32 v31, 0xffff0000, v183
	v_add_f32_e32 v18, v18, v21
	v_lshlrev_b32_e32 v26, 16, v184
	v_mov_b32_e32 v27, v31
	v_add_f32_e32 v29, v29, v31
	v_and_b32_e32 v36, s0, v38
	v_add_f32_e32 v18, v19, v18
	v_and_b32_e32 v20, 0xffff0000, v184
	v_pk_mul_f32 v[38:39], v[26:27], v[26:27]
	v_add_f32_e32 v27, v29, v26
	v_lshlrev_b32_e32 v21, 16, v185
	v_add_f32_e32 v18, v39, v18
	v_add_f32_e32 v27, v27, v20
	v_and_b32_e32 v29, 64, v181
	v_add_f32_e32 v18, v38, v18
	v_pk_mul_f32 v[40:41], v[20:21], v[20:21]
	v_add_f32_e32 v39, v27, v21
	v_xor_b32_e32 v27, 1, v181
	v_add_u32_e32 v29, 64, v29
	v_and_b32_e32 v19, 0xffff0000, v185
	v_add_f32_e32 v18, v40, v18
	v_cmp_lt_i32_e32 vcc, v27, v29
	v_add_f32_e32 v18, v41, v18
	v_mul_f32_e32 v38, v19, v19
	v_cndmask_b32_e32 v27, v181, v27, vcc
	v_lshlrev_b32_e32 v27, 2, v27
	v_pk_add_f32 v[38:39], v[38:39], v[18:19]
	ds_bpermute_b32 v41, v27, v39
	ds_bpermute_b32 v40, v27, v38
	v_xor_b32_e32 v35, 2, v181
	v_cmp_lt_i32_e32 vcc, v35, v29
	v_and_b32_e32 v30, s0, v182
	v_mov_b32_e32 v32, v36
	v_cndmask_b32_e32 v29, v181, v35, vcc
	v_lshlrev_b32_e32 v29, 2, v29
	s_waitcnt lgkmcnt(0)
	v_pk_add_f32 v[38:39], v[38:39], v[40:41]
	ds_bpermute_b32 v41, v29, v39
	ds_bpermute_b32 v40, v29, v38
	s_waitcnt lgkmcnt(0)
	v_pk_add_f32 v[40:41], v[38:39], v[40:41]
	s_nop 0
	v_pk_mul_f32 v[38:39], v[40:41], s[22:23] op_sel_hi:[1,0]
	v_pk_fma_f32 v[36:37], v[40:41], s[22:23], v[36:37] op_sel_hi:[1,0,1] neg_lo:[1,0,0] neg_hi:[1,0,0]
	v_fma_f32 v18, -v39, v39, v38
	v_max_f32_e32 v18, 0, v18
	v_add_f32_e32 v18, 0x358637bd, v18
	v_cmp_gt_f32_e32 vcc, s33, v18
	v_mul_f32_e32 v27, 0x4b800000, v18
	v_sub_f32_e32 v29, v174, v39
	v_cndmask_b32_e32 v18, v18, v27, vcc
	v_rsq_f32_e32 v18, v18
	v_sub_f32_e32 v19, v19, v39
	v_mul_f32_e32 v27, 0x45800000, v18
	v_cndmask_b32_e32 v18, v18, v27, vcc
	v_mul_f32_e32 v29, v29, v18
	v_lshlrev_b32_e32 v27, 1, v45
	v_bfe_u32 v35, v29, 16, 1
	v_ashrrev_i32_e32 v45, 1, v43
	v_and_b32_e32 v27, 14, v27
	v_add3_u32 v29, v29, v35, s15
	v_lshl_add_u32 v35, v46, 8, 32
	v_and_b32_e32 v46, -16, v45
	v_add3_u32 v174, v35, v46, v27
	ds_write_b16_d16_hi v174, v29 offset:55296
	v_mul_f32_e64 v215, -v39, v18
	v_fma_f32 v29, v173, v18, v215
	v_cvt_pk_bf16_f32 v29, v29, v29
	v_bitop3_b32 v173, v45, 16, -16 bitop3:0x6c
	v_add3_u32 v175, v35, v173, v27
	ds_write_b16 v175, v29 offset:55552
	v_fma_f32 v29, v172, v18, v215
	v_cvt_pk_bf16_f32 v29, v29, v29
	v_bitop3_b32 v172, v45, 32, -16 bitop3:0x6c
	v_add3_u32 v176, v35, v172, v27
	ds_write_b16 v176, v29 offset:55808
	v_fma_f32 v29, v171, v18, v215
	v_cvt_pk_bf16_f32 v29, v29, v29
	v_bitop3_b32 v171, v45, 48, -16 bitop3:0x6c
	v_add3_u32 v177, v35, v171, v27
	ds_write_b16 v177, v29 offset:56064
	v_fma_f32 v29, v170, v18, v215
	v_cvt_pk_bf16_f32 v29, v29, v29
	v_bitop3_b32 v170, v45, 64, -16 bitop3:0x6c
	v_add3_u32 v178, v35, v170, v27
	ds_write_b16 v178, v29 offset:56320
	v_fma_f32 v29, v169, v18, v215
	v_cvt_pk_bf16_f32 v29, v29, v29
	v_bitop3_b32 v169, v45, s34, -16 bitop3:0x6c
	v_add3_u32 v179, v35, v169, v27
	ds_write_b16 v179, v29 offset:56576
	v_fma_f32 v29, v167, v18, v215
	v_cvt_pk_bf16_f32 v29, v29, v29
	v_bitop3_b32 v167, v45, s31, -16 bitop3:0x6c
	v_add3_u32 v182, v35, v167, v27
	ds_write_b16 v182, v29 offset:56832
	v_fma_f32 v29, v165, v18, v215
	v_cvt_pk_bf16_f32 v29, v29, v29
	v_bitop3_b32 v165, v45, s13, -16 bitop3:0x6c
	v_add3_u32 v183, v35, v165, v27
	ds_write_b16 v183, v29 offset:57088
	v_fma_f32 v29, v168, v18, v215
	v_cvt_pk_bf16_f32 v29, v29, v29
	v_bitop3_b32 v168, v45, s12, -16 bitop3:0x6c
	v_add3_u32 v184, v35, v168, v27
	ds_write_b16 v184, v29 offset:57344
	v_fma_f32 v29, v166, v18, v215
	v_cvt_pk_bf16_f32 v29, v29, v29
	v_bitop3_b32 v166, v45, s35, -16 bitop3:0x6c
	v_add3_u32 v185, v35, v166, v27
	ds_write_b16 v185, v29 offset:57600
	v_fma_f32 v29, v164, v18, v215
	v_cvt_pk_bf16_f32 v29, v29, v29
	v_bitop3_b32 v164, v45, s38, -16 bitop3:0x6c
	v_add3_u32 v186, v35, v164, v27
	ds_write_b16 v186, v29 offset:57856
	v_fma_f32 v29, v153, v18, v215
	v_cvt_pk_bf16_f32 v29, v29, v29
	v_bitop3_b32 v153, v45, s39, -16 bitop3:0x6c
	v_add3_u32 v187, v35, v153, v27
	ds_write_b16 v187, v29 offset:58112
	v_fma_f32 v29, v152, v18, v215
	v_cvt_pk_bf16_f32 v29, v29, v29
	v_bitop3_b32 v152, v45, s16, -16 bitop3:0x6c
	v_add3_u32 v188, v35, v152, v27
	ds_write_b16 v188, v29 offset:58368
	v_fma_f32 v29, v151, v18, v215
	v_cvt_pk_bf16_f32 v29, v29, v29
	v_bitop3_b32 v151, v45, s40, -16 bitop3:0x6c
	v_add3_u32 v189, v35, v151, v27
	ds_write_b16 v189, v29 offset:58624
	v_fma_f32 v29, v148, v18, v215
	v_cvt_pk_bf16_f32 v29, v29, v29
	v_bitop3_b32 v148, v45, s41, -16 bitop3:0x6c
	v_add3_u32 v190, v35, v148, v27
	ds_write_b16 v190, v29 offset:58880
	v_sub_f32_e32 v29, v146, v39
	v_mul_f32_e32 v29, v29, v18
	v_bfe_u32 v146, v29, 16, 1
	v_bitop3_b32 v45, v45, s42, -16 bitop3:0x6c
	v_add_u32_e32 v38, 0xd800, v35
	v_add3_u32 v29, v29, v146, s15
	v_add3_u32 v35, v35, v45, v27
	ds_write_b16_d16_hi v35, v29 offset:59136
	v_fma_f32 v29, v150, v18, v215
	v_cvt_pk_bf16_f32 v29, v29, v29
	ds_write_b16 v174, v29 offset:59392
	v_fma_f32 v29, v149, v18, v215
	v_cvt_pk_bf16_f32 v29, v29, v29
	ds_write_b16 v175, v29 offset:59648
	v_fma_f32 v29, v147, v18, v215
	v_cvt_pk_bf16_f32 v29, v29, v29
	ds_write_b16 v176, v29 offset:59904
	v_fma_f32 v29, v145, v18, v215
	v_cvt_pk_bf16_f32 v29, v29, v29
	ds_write_b16 v177, v29 offset:60160
	v_fma_f32 v29, v143, v18, v215
	v_cvt_pk_bf16_f32 v29, v29, v29
	ds_write_b16 v178, v29 offset:60416
	v_fma_f32 v29, v141, v18, v215
	v_cvt_pk_bf16_f32 v29, v29, v29
	ds_write_b16 v179, v29 offset:60672
	v_fma_f32 v29, v139, v18, v215
	v_cvt_pk_bf16_f32 v29, v29, v29
	ds_write_b16 v182, v29 offset:60928
	v_fma_f32 v29, v137, v18, v215
	v_cvt_pk_bf16_f32 v29, v29, v29
	ds_write_b16 v183, v29 offset:61184
	v_fma_f32 v29, v144, v18, v215
	v_cvt_pk_bf16_f32 v29, v29, v29
	ds_write_b16 v184, v29 offset:61440
	v_fma_f32 v29, v142, v18, v215
	v_cvt_pk_bf16_f32 v29, v29, v29
	ds_write_b16 v185, v29 offset:61696
	v_fma_f32 v29, v140, v18, v215
	v_cvt_pk_bf16_f32 v29, v29, v29
	ds_write_b16 v186, v29 offset:61952
	v_fma_f32 v29, v138, v18, v215
	v_cvt_pk_bf16_f32 v29, v29, v29
	ds_write_b16 v187, v29 offset:62208
	v_fma_f32 v29, v133, v18, v215
	v_cvt_pk_bf16_f32 v29, v29, v29
	ds_write_b16 v188, v29 offset:62464
	v_fma_f32 v29, v131, v18, v215
	v_cvt_pk_bf16_f32 v29, v29, v29
	ds_write_b16 v189, v29 offset:62720
	v_fma_f32 v29, v64, v18, v215
	v_cvt_pk_bf16_f32 v29, v29, v29
	ds_write_b16 v190, v29 offset:62976
	v_fma_f32 v29, v62, v18, v215
	v_cvt_pk_bf16_f32 v29, v29, v29
	ds_write_b16 v35, v29 offset:63232
	v_fma_f32 v29, v136, v18, v215
	v_cvt_pk_bf16_f32 v29, v29, v29
	ds_write_b16 v174, v29 offset:63488
	v_fma_f32 v29, v132, v18, v215
	v_cvt_pk_bf16_f32 v29, v29, v29
	ds_write_b16 v175, v29 offset:63744
	v_fma_f32 v29, v65, v18, v215
	v_cvt_pk_bf16_f32 v29, v29, v29
	ds_write_b16 v176, v29 offset:64000
	v_fma_f32 v29, v63, v18, v215
	v_cvt_pk_bf16_f32 v29, v29, v29
	ds_write_b16 v177, v29 offset:64256
	v_fma_f32 v29, v60, v18, v215
	v_cvt_pk_bf16_f32 v29, v29, v29
	ds_write_b16 v178, v29 offset:64512
	v_fma_f32 v29, v59, v18, v215
	v_cvt_pk_bf16_f32 v29, v29, v29
	ds_write_b16 v179, v29 offset:64768
	v_fma_f32 v29, v57, v18, v215
	v_cvt_pk_bf16_f32 v29, v29, v29
	ds_write_b16 v182, v29 offset:65024
	v_fma_f32 v29, v55, v18, v215
	v_cvt_pk_bf16_f32 v29, v29, v29
	ds_write_b16 v183, v29 offset:65280
	v_fma_f32 v29, v61, v18, v215
	v_cvt_pk_bf16_f32 v29, v29, v29
	v_add3_u32 v35, v38, v168, v27
	ds_write_b16 v35, v29 offset:10240
	v_fma_f32 v29, v58, v18, v215
	v_cvt_pk_bf16_f32 v29, v29, v29
	v_add3_u32 v55, v38, v166, v27
	ds_write_b16 v55, v29 offset:10496
	v_fma_f32 v29, v56, v18, v215
	v_cvt_pk_bf16_f32 v29, v29, v29
	v_add3_u32 v56, v38, v164, v27
	ds_write_b16 v56, v29 offset:10752
	v_fma_f32 v29, v54, v18, v215
	v_cvt_pk_bf16_f32 v29, v29, v29
	v_add3_u32 v54, v38, v153, v27
	ds_write_b16 v54, v29 offset:11008
	v_fma_f32 v29, v53, v18, v215
	v_cvt_pk_bf16_f32 v29, v29, v29
	v_add3_u32 v53, v38, v152, v27
	ds_write_b16 v53, v29 offset:11264
	v_fma_f32 v29, v51, v18, v215
	v_cvt_pk_bf16_f32 v29, v29, v29
	v_add3_u32 v51, v38, v151, v27
	ds_write_b16 v51, v29 offset:11520
	v_fma_f32 v29, v49, v18, v215
	v_cvt_pk_bf16_f32 v29, v29, v29
	v_add3_u32 v49, v38, v148, v27
	ds_write_b16 v49, v29 offset:11776
	v_fma_f32 v29, v47, v18, v215
	v_cvt_pk_bf16_f32 v29, v29, v29
	v_add3_u32 v45, v38, v45, v27
	ds_write_b16 v45, v29 offset:12032
	v_fma_f32 v29, v52, v18, v215
	v_cvt_pk_bf16_f32 v29, v29, v29
	v_add3_u32 v46, v38, v46, v27
	ds_write_b16 v46, v29 offset:12288
	v_fma_f32 v29, v50, v18, v215
	v_cvt_pk_bf16_f32 v29, v29, v29
	v_add3_u32 v46, v38, v173, v27
	ds_write_b16 v46, v29 offset:12544
	v_fma_f32 v29, v48, v18, v215
	v_cvt_pk_bf16_f32 v29, v29, v29
	v_add3_u32 v46, v38, v172, v27
	ds_write_b16 v46, v29 offset:12800
	v_mul_f32_e32 v29, v37, v18
	v_bfe_u32 v36, v29, 16, 1
	v_add3_u32 v29, v29, v36, s15
	v_add3_u32 v36, v38, v171, v27
	ds_write_b16_d16_hi v36, v29 offset:13056
	v_fma_f32 v29, v34, v18, v215
	v_cvt_pk_bf16_f32 v29, v29, v29
	v_add3_u32 v34, v38, v170, v27
	ds_write_b16 v34, v29 offset:13312
	v_sub_f32_e32 v29, v24, v39
	v_pk_fma_f32 v[24:25], v[40:41], s[22:23], v[24:25] op_sel_hi:[1,0,1] neg_lo:[1,0,0] neg_hi:[1,0,0]
	v_mul_f32_e32 v29, v29, v18
	v_mul_f32_e32 v24, v25, v18
	v_bfe_u32 v34, v29, 16, 1
	v_bfe_u32 v25, v24, 16, 1
	v_add3_u32 v29, v29, v34, s15
	v_add3_u32 v34, v38, v169, v27
	v_add3_u32 v24, v24, v25, s15
	v_add3_u32 v25, v38, v167, v27
	ds_write_b16_d16_hi v34, v29 offset:13568
	ds_write_b16_d16_hi v25, v24 offset:13824
	v_pk_fma_f32 v[24:25], v[40:41], s[22:23], v[32:33] op_sel_hi:[1,0,1] neg_lo:[1,0,0] neg_hi:[1,0,0]
	v_and_b32_e32 v133, 15, v43
	v_mul_f32_e32 v24, v25, v18
	v_bfe_u32 v25, v24, 16, 1
	v_add3_u32 v24, v24, v25, s15
	v_add3_u32 v25, v38, v165, v27
	ds_write_b16_d16_hi v25, v24 offset:14080
	v_fma_f32 v24, v28, v18, v215
	v_cvt_pk_bf16_f32 v24, v24, v24
	ds_write_b16 v35, v24 offset:14336
	v_sub_f32_e32 v24, v22, v39
	v_pk_fma_f32 v[22:23], v[40:41], s[22:23], v[22:23] op_sel_hi:[1,0,1] neg_lo:[1,0,0] neg_hi:[1,0,0]
	v_mul_f32_e32 v24, v24, v18
	v_mul_f32_e32 v22, v23, v18
	v_bfe_u32 v25, v24, 16, 1
	v_bfe_u32 v23, v22, 16, 1
	v_add3_u32 v24, v24, v25, s15
	v_add3_u32 v22, v22, v23, s15
	ds_write_b16_d16_hi v55, v24 offset:14592
	ds_write_b16_d16_hi v56, v22 offset:14848
	v_pk_fma_f32 v[22:23], v[40:41], s[22:23], v[30:31] op_sel_hi:[1,0,1] neg_lo:[1,0,0] neg_hi:[1,0,0]
	s_nop 0
	v_mul_f32_e32 v22, v23, v18
	v_bfe_u32 v23, v22, 16, 1
	v_add3_u32 v22, v22, v23, s15
	ds_write_b16_d16_hi v54, v22 offset:15104
	v_fma_f32 v22, v26, v18, v215
	v_cvt_pk_bf16_f32 v22, v22, v22
	ds_write_b16 v53, v22 offset:15360
	v_sub_f32_e32 v22, v20, v39
	v_pk_fma_f32 v[20:21], v[40:41], s[22:23], v[20:21] op_sel_hi:[1,0,1] neg_lo:[1,0,0] neg_hi:[1,0,0]
	v_mul_f32_e32 v22, v22, v18
	v_mul_f32_e32 v20, v21, v18
	v_mul_f32_e32 v18, v19, v18
	v_bfe_u32 v23, v22, 16, 1
	v_bfe_u32 v21, v20, 16, 1
	v_bfe_u32 v19, v18, 16, 1
	v_add3_u32 v22, v22, v23, s15
	v_add3_u32 v20, v20, v21, s15
	v_add3_u32 v18, v18, v19, s15
	ds_write_b16_d16_hi v51, v22 offset:15616
	ds_write_b16_d16_hi v49, v20 offset:15872
	ds_write_b16_d16_hi v45, v18 offset:16128
	v_lshrrev_b32_e32 v18, 1, v43
	v_and_b32_e32 v18, 32, v18
	v_lshl_or_b32 v132, v44, 6, v18
	v_or_b32_e32 v18, v132, v134
	v_lshl_add_u32 v131, v18, 8, 32
	v_bitop3_b32 v18, v42, v133, 1 bitop3:0x6c
	v_lshl_add_u32 v18, v18, 4, v131
	s_waitcnt lgkmcnt(0)
	s_barrier
	ds_read_b128 v[136:139], v18 offset:55296
	s_waitcnt lgkmcnt(0)
	v_mfma_f32_32x32x16_bf16 v[50:65], v[136:139], v[2:5], 0
	v_mfma_f32_32x32x16_bf16 v[34:49], v[136:139], v[6:9], 0
	v_mfma_f32_32x32x16_bf16 v[18:33], v[136:139], v[10:13], 0
	v_mfma_f32_32x32x16_bf16 v[2:17], v[136:139], v[14:17], 0
	v_bitop3_b32 v136, v135, v133, 2 bitop3:0x36
	v_lshl_add_u32 v136, v136, 4, v131
	ds_read_b128 v[136:139], v136 offset:55296
	s_waitcnt lgkmcnt(0)
	v_mfma_f32_32x32x16_bf16 v[50:65], v[136:139], v[114:117], v[50:65]
	v_bitop3_b32 v114, v135, v133, 4 bitop3:0x36
	v_lshl_add_u32 v114, v114, 4, v131
	ds_read_b128 v[114:117], v114 offset:55296
	v_mfma_f32_32x32x16_bf16 v[34:49], v[136:139], v[118:121], v[34:49]
	v_mfma_f32_32x32x16_bf16 v[18:33], v[136:139], v[122:125], v[18:33]
	s_waitcnt lgkmcnt(0)
	v_mfma_f32_32x32x16_bf16 v[34:49], v[114:117], v[102:105], v[34:49]
	v_bitop3_b32 v102, v135, v133, 6 bitop3:0x36
	v_lshl_add_u32 v102, v102, 4, v131
	ds_read_b128 v[102:105], v102 offset:55296
	v_mfma_f32_32x32x16_bf16 v[2:17], v[136:139], v[126:129], v[2:17]
	v_mfma_f32_32x32x16_bf16 v[18:33], v[114:117], v[106:109], v[18:33]
	s_waitcnt lgkmcnt(0)
	v_mfma_f32_32x32x16_bf16 v[34:49], v[102:105], v[90:93], v[34:49]
	v_bitop3_b32 v90, v135, v133, 8 bitop3:0x36
	v_lshl_add_u32 v90, v90, 4, v131
	ds_read_b128 v[90:93], v90 offset:55296
	v_mfma_f32_32x32x16_bf16 v[2:17], v[114:117], v[110:113], v[2:17]
	v_mfma_f32_32x32x16_bf16 v[18:33], v[102:105], v[94:97], v[18:33]
	v_mfma_f32_32x32x16_bf16 v[2:17], v[102:105], v[98:101], v[2:17]
	v_lshlrev_b32_e32 v104, 7, v130
	v_or_b32_e32 v102, v104, v134
	v_ashrrev_i32_e32 v103, 31, v102
	v_lshlrev_b64 v[106:107], 2, v[102:103]
	v_lshl_or_b32 v98, v135, 2, v132
	v_or_b32_e32 v100, s3, v134
	v_mov_b32_e32 v101, s5
	s_waitcnt lgkmcnt(0)
	v_mfma_f32_32x32x16_bf16 v[18:33], v[90:93], v[82:85], v[18:33]
	v_bitop3_b32 v82, v135, v133, 10 bitop3:0x36
	v_lshl_add_u32 v82, v82, 4, v131
	ds_read_b128 v[82:85], v82 offset:55296
	v_lshl_add_u64 v[108:109], s[6:7], 0, v[106:107]
	v_lshl_add_u64 v[106:107], s[92:93], 0, v[106:107]
	v_ashrrev_i32_e32 v99, 31, v98
	v_lshlrev_b64 v[98:99], 1, v[98:99]
	v_mfma_f32_32x32x16_bf16 v[2:17], v[90:93], v[86:89], v[2:17]
	s_add_i32 s3, s3, s18
	s_cmpk_gt_i32 s4, 0x7f
	s_waitcnt lgkmcnt(0)
	v_mfma_f32_32x32x16_bf16 v[18:33], v[82:85], v[74:77], v[18:33]
	v_bitop3_b32 v74, v135, v133, 12 bitop3:0x36
	v_lshl_add_u32 v74, v74, 4, v131
	ds_read_b128 v[74:77], v74 offset:55296
	v_mfma_f32_32x32x16_bf16 v[2:17], v[82:85], v[78:81], v[2:17]
	s_waitcnt lgkmcnt(0)
	v_mfma_f32_32x32x16_bf16 v[2:17], v[74:77], v[70:73], v[2:17]
	v_bitop3_b32 v70, v135, v133, 14 bitop3:0x36
	v_lshl_add_u32 v70, v70, 4, v131
	ds_read_b128 v[70:73], v70 offset:55296
	v_ashrrev_i32_e32 v133, 31, v132
	s_waitcnt lgkmcnt(0)
	v_mfma_f32_32x32x16_bf16 v[2:17], v[70:73], v[66:69], v[2:17]
	v_lshlrev_b64 v[66:67], 2, v[132:133]
	v_lshl_add_u64 v[68:69], s[10:11], 0, v[66:67]
	v_lshl_add_u64 v[66:67], s[36:37], 0, v[66:67]
	v_lshl_add_u64 v[68:69], v[68:69], 0, v[154:155]
	v_lshl_add_u64 v[70:71], v[66:67], 0, v[154:155]
	global_load_dwordx4 v[90:93], v[68:69], off
	global_load_dwordx4 v[94:97], v[70:71], off
	global_load_dwordx4 v[82:85], v[68:69], off offset:32
	global_load_dwordx4 v[86:89], v[70:71], off offset:32
	global_load_dwordx4 v[74:77], v[68:69], off offset:64
	global_load_dwordx4 v[78:81], v[70:71], off offset:64
	s_nop 0
	global_load_dwordx4 v[66:69], v[68:69], off offset:96
	s_nop 0
	global_load_dwordx4 v[70:73], v[70:71], off offset:96
	s_nop 0
	global_load_dword v118, v[108:109], off
	global_load_dword v119, v[108:109], off offset:128
	global_load_dword v120, v[108:109], off offset:256
	global_load_dword v121, v[108:109], off offset:384
	global_load_dword v122, v[106:107], off
	global_load_dword v123, v[106:107], off offset:128
	global_load_dword v124, v[106:107], off offset:256
	global_load_dword v125, v[106:107], off offset:384
	v_lshlrev_b64 v[110:111], 11, v[100:101]
	v_lshl_add_u64 v[110:111], s[62:63], 0, v[110:111]
	v_lshl_add_u64 v[110:111], v[110:111], 0, v[98:99]
	v_add_co_u32_e32 v112, vcc, 0x10000, v110
	s_nop 1
	v_addc_co_u32_e32 v113, vcc, 0, v111, vcc
	v_add_co_u32_e32 v114, vcc, 0x20000, v110
	s_nop 1
	v_addc_co_u32_e32 v115, vcc, 0, v111, vcc
	v_add_co_u32_e32 v116, vcc, 0x30000, v110
	s_nop 1
	v_addc_co_u32_e32 v117, vcc, 0, v111, vcc
	s_barrier
	v_and_b32_e32 v126, 31, v0
	v_lshlrev_b32_e32 v136, 6, v126
	v_bfe_u32 v127, v0, 5, 1
	v_lshl_add_u32 v136, v127, 3, v136
	v_lshrrev_b32_e32 v134, 6, v0
	v_lshl_add_u32 v136, v134, 13, v136
	v_add_u32_e32 v136, 0xd820, v136
	v_bfe_u32 v126, v0, 1, 2
	v_xor_b32_e32 v127, 0, v126
	v_lshl_add_u32 v128, v127, 4, v136
	v_xor_b32_e32 v127, 1, v126
	v_lshl_add_u32 v129, v127, 4, v136
	v_xor_b32_e32 v127, 2, v126
	v_lshl_add_u32 v130, v127, 4, v136
	v_xor_b32_e32 v127, 3, v126
	v_lshl_add_u32 v131, v127, 4, v136
	v_bfe_u32 v135, v0, 2, 4
	v_lshlrev_b32_e32 v132, 6, v135
	v_and_b32_e32 v127, 3, v0
	v_bfe_u32 v126, v0, 3, 2
	v_xor_b32_e32 v126, v127, v126
	v_lshl_add_u32 v132, v126, 4, v132
	v_lshl_add_u32 v132, v134, 13, v132
	v_add_u32_e32 v132, 0xd820, v132
	v_and_b32_e32 v133, -32, v100
	v_add_u32_e32 v133, v133, v135
	v_lshlrev_b32_e32 v133, 11, v133
	v_lshl_add_u32 v133, v134, 6, v133
	v_lshl_add_u32 v133, v127, 4, v133
	s_waitcnt vmcnt(0)
	s_nop 1
	v_permlane32_swap_b32 v216, v218
	v_permlane32_swap_b32 v217, v219
	v_permlane32_swap_b32 v220, v222
	v_permlane32_swap_b32 v221, v223
	v_permlane32_swap_b32 v224, v226
	v_permlane32_swap_b32 v225, v227
	v_permlane32_swap_b32 v228, v230
	v_permlane32_swap_b32 v229, v231
	v_permlane32_swap_b32 v232, v234
	v_permlane32_swap_b32 v233, v235
	v_permlane32_swap_b32 v236, v238
	v_permlane32_swap_b32 v237, v239
	v_permlane32_swap_b32 v252, v254
	v_permlane32_swap_b32 v253, v255
	v_mul_f32_e32 v126, v94, v118
	v_fmac_f32_e32 v126, v50, v90
	v_add_f32_e32 v50, v122, v126
	v_lshlrev_b32_e32 v127, 16, v216
	v_mul_f32_e32 v50, v50, v127
	v_mul_f32_e32 v126, v95, v118
	v_fmac_f32_e32 v126, v51, v91
	v_add_f32_e32 v51, v122, v126
	v_and_b32_e32 v127, 0xffff0000, v216
	v_mul_f32_e32 v51, v51, v127
	v_mul_f32_e32 v126, v96, v118
	v_fmac_f32_e32 v126, v52, v92
	v_add_f32_e32 v52, v122, v126
	v_lshlrev_b32_e32 v127, 16, v217
	v_mul_f32_e32 v52, v52, v127
	v_mul_f32_e32 v126, v97, v118
	v_fmac_f32_e32 v126, v53, v93
	v_add_f32_e32 v53, v122, v126
	v_and_b32_e32 v127, 0xffff0000, v217
	v_mul_f32_e32 v53, v53, v127
	v_cvt_pk_bf16_f32 v50, v50, v51
	v_cvt_pk_bf16_f32 v51, v52, v53
	ds_write_b64 v128, v[50:51] offset:0
	v_mul_f32_e32 v126, v86, v118
	v_fmac_f32_e32 v126, v54, v82
	v_add_f32_e32 v54, v122, v126
	v_lshlrev_b32_e32 v127, 16, v218
	v_mul_f32_e32 v54, v54, v127
	v_mul_f32_e32 v126, v87, v118
	v_fmac_f32_e32 v126, v55, v83
	v_add_f32_e32 v55, v122, v126
	v_and_b32_e32 v127, 0xffff0000, v218
	v_mul_f32_e32 v55, v55, v127
	v_mul_f32_e32 v126, v88, v118
	v_fmac_f32_e32 v126, v56, v84
	v_add_f32_e32 v56, v122, v126
	v_lshlrev_b32_e32 v127, 16, v219
	v_mul_f32_e32 v56, v56, v127
	v_mul_f32_e32 v126, v89, v118
	v_fmac_f32_e32 v126, v57, v85
	v_add_f32_e32 v57, v122, v126
	v_and_b32_e32 v127, 0xffff0000, v219
	v_mul_f32_e32 v57, v57, v127
	v_cvt_pk_bf16_f32 v54, v54, v55
	v_cvt_pk_bf16_f32 v55, v56, v57
	ds_write_b64 v129, v[54:55] offset:0
	v_mul_f32_e32 v126, v78, v118
	v_fmac_f32_e32 v126, v58, v74
	v_add_f32_e32 v58, v122, v126
	v_lshlrev_b32_e32 v127, 16, v220
	v_mul_f32_e32 v58, v58, v127
	v_mul_f32_e32 v126, v79, v118
	v_fmac_f32_e32 v126, v59, v75
	v_add_f32_e32 v59, v122, v126
	v_and_b32_e32 v127, 0xffff0000, v220
	v_mul_f32_e32 v59, v59, v127
	v_mul_f32_e32 v126, v80, v118
	v_fmac_f32_e32 v126, v60, v76
	v_add_f32_e32 v60, v122, v126
	v_lshlrev_b32_e32 v127, 16, v221
	v_mul_f32_e32 v60, v60, v127
	v_mul_f32_e32 v126, v81, v118
	v_fmac_f32_e32 v126, v61, v77
	v_add_f32_e32 v61, v122, v126
	v_and_b32_e32 v127, 0xffff0000, v221
	v_mul_f32_e32 v61, v61, v127
	v_cvt_pk_bf16_f32 v58, v58, v59
	v_cvt_pk_bf16_f32 v59, v60, v61
	ds_write_b64 v130, v[58:59] offset:0
	v_mul_f32_e32 v126, v70, v118
	v_fmac_f32_e32 v126, v62, v66
	v_add_f32_e32 v62, v122, v126
	v_lshlrev_b32_e32 v127, 16, v222
	v_mul_f32_e32 v62, v62, v127
	v_mul_f32_e32 v126, v71, v118
	v_fmac_f32_e32 v126, v63, v67
	v_add_f32_e32 v63, v122, v126
	v_and_b32_e32 v127, 0xffff0000, v222
	v_mul_f32_e32 v63, v63, v127
	v_mul_f32_e32 v126, v72, v118
	v_fmac_f32_e32 v126, v64, v68
	v_add_f32_e32 v64, v122, v126
	v_lshlrev_b32_e32 v127, 16, v223
	v_mul_f32_e32 v64, v64, v127
	v_mul_f32_e32 v126, v73, v118
	v_fmac_f32_e32 v126, v65, v69
	v_add_f32_e32 v65, v122, v126
	v_and_b32_e32 v127, 0xffff0000, v223
	v_mul_f32_e32 v65, v65, v127
	v_cvt_pk_bf16_f32 v62, v62, v63
	v_cvt_pk_bf16_f32 v63, v64, v65
	ds_write_b64 v131, v[62:63] offset:0
	v_mul_f32_e32 v126, v94, v119
	v_fmac_f32_e32 v126, v34, v90
	v_add_f32_e32 v34, v123, v126
	v_lshlrev_b32_e32 v127, 16, v224
	v_mul_f32_e32 v34, v34, v127
	v_mul_f32_e32 v126, v95, v119
	v_fmac_f32_e32 v126, v35, v91
	v_add_f32_e32 v35, v123, v126
	v_and_b32_e32 v127, 0xffff0000, v224
	v_mul_f32_e32 v35, v35, v127
	v_mul_f32_e32 v126, v96, v119
	v_fmac_f32_e32 v126, v36, v92
	v_add_f32_e32 v36, v123, v126
	v_lshlrev_b32_e32 v127, 16, v225
	v_mul_f32_e32 v36, v36, v127
	v_mul_f32_e32 v126, v97, v119
	v_fmac_f32_e32 v126, v37, v93
	v_add_f32_e32 v37, v123, v126
	v_and_b32_e32 v127, 0xffff0000, v225
	v_mul_f32_e32 v37, v37, v127
	v_cvt_pk_bf16_f32 v34, v34, v35
	v_cvt_pk_bf16_f32 v35, v36, v37
	ds_write_b64 v128, v[34:35] offset:2048
	v_mul_f32_e32 v126, v86, v119
	v_fmac_f32_e32 v126, v38, v82
	v_add_f32_e32 v38, v123, v126
	v_lshlrev_b32_e32 v127, 16, v226
	v_mul_f32_e32 v38, v38, v127
	v_mul_f32_e32 v126, v87, v119
	v_fmac_f32_e32 v126, v39, v83
	v_add_f32_e32 v39, v123, v126
	v_and_b32_e32 v127, 0xffff0000, v226
	v_mul_f32_e32 v39, v39, v127
	v_mul_f32_e32 v126, v88, v119
	v_fmac_f32_e32 v126, v40, v84
	v_add_f32_e32 v40, v123, v126
	v_lshlrev_b32_e32 v127, 16, v227
	v_mul_f32_e32 v40, v40, v127
	v_mul_f32_e32 v126, v89, v119
	v_fmac_f32_e32 v126, v41, v85
	v_add_f32_e32 v41, v123, v126
	v_and_b32_e32 v127, 0xffff0000, v227
	v_mul_f32_e32 v41, v41, v127
	v_cvt_pk_bf16_f32 v38, v38, v39
	v_cvt_pk_bf16_f32 v39, v40, v41
	ds_write_b64 v129, v[38:39] offset:2048
	v_mul_f32_e32 v126, v78, v119
	v_fmac_f32_e32 v126, v42, v74
	v_add_f32_e32 v42, v123, v126
	v_lshlrev_b32_e32 v127, 16, v228
	v_mul_f32_e32 v42, v42, v127
	v_mul_f32_e32 v126, v79, v119
	v_fmac_f32_e32 v126, v43, v75
	v_add_f32_e32 v43, v123, v126
	v_and_b32_e32 v127, 0xffff0000, v228
	v_mul_f32_e32 v43, v43, v127
	v_mul_f32_e32 v126, v80, v119
	v_fmac_f32_e32 v126, v44, v76
	v_add_f32_e32 v44, v123, v126
	v_lshlrev_b32_e32 v127, 16, v229
	v_mul_f32_e32 v44, v44, v127
	v_mul_f32_e32 v126, v81, v119
	v_fmac_f32_e32 v126, v45, v77
	v_add_f32_e32 v45, v123, v126
	v_and_b32_e32 v127, 0xffff0000, v229
	v_mul_f32_e32 v45, v45, v127
	v_cvt_pk_bf16_f32 v42, v42, v43
	v_cvt_pk_bf16_f32 v43, v44, v45
	ds_write_b64 v130, v[42:43] offset:2048
	v_mul_f32_e32 v126, v70, v119
	v_fmac_f32_e32 v126, v46, v66
	v_add_f32_e32 v46, v123, v126
	v_lshlrev_b32_e32 v127, 16, v230
	v_mul_f32_e32 v46, v46, v127
	v_mul_f32_e32 v126, v71, v119
	v_fmac_f32_e32 v126, v47, v67
	v_add_f32_e32 v47, v123, v126
	v_and_b32_e32 v127, 0xffff0000, v230
	v_mul_f32_e32 v47, v47, v127
	v_mul_f32_e32 v126, v72, v119
	v_fmac_f32_e32 v126, v48, v68
	v_add_f32_e32 v48, v123, v126
	v_lshlrev_b32_e32 v127, 16, v231
	v_mul_f32_e32 v48, v48, v127
	v_mul_f32_e32 v126, v73, v119
	v_fmac_f32_e32 v126, v49, v69
	v_add_f32_e32 v49, v123, v126
	v_and_b32_e32 v127, 0xffff0000, v231
	v_mul_f32_e32 v49, v49, v127
	v_cvt_pk_bf16_f32 v46, v46, v47
	v_cvt_pk_bf16_f32 v47, v48, v49
	ds_write_b64 v131, v[46:47] offset:2048
	v_mul_f32_e32 v126, v94, v120
	v_fmac_f32_e32 v126, v18, v90
	v_add_f32_e32 v18, v124, v126
	v_lshlrev_b32_e32 v127, 16, v232
	v_mul_f32_e32 v18, v18, v127
	v_mul_f32_e32 v126, v95, v120
	v_fmac_f32_e32 v126, v19, v91
	v_add_f32_e32 v19, v124, v126
	v_and_b32_e32 v127, 0xffff0000, v232
	v_mul_f32_e32 v19, v19, v127
	v_mul_f32_e32 v126, v96, v120
	v_fmac_f32_e32 v126, v20, v92
	v_add_f32_e32 v20, v124, v126
	v_lshlrev_b32_e32 v127, 16, v233
	v_mul_f32_e32 v20, v20, v127
	v_mul_f32_e32 v126, v97, v120
	v_fmac_f32_e32 v126, v21, v93
	v_add_f32_e32 v21, v124, v126
	v_and_b32_e32 v127, 0xffff0000, v233
	v_mul_f32_e32 v21, v21, v127
	v_cvt_pk_bf16_f32 v18, v18, v19
	v_cvt_pk_bf16_f32 v19, v20, v21
	ds_write_b64 v128, v[18:19] offset:4096
	v_mul_f32_e32 v126, v86, v120
	v_fmac_f32_e32 v126, v22, v82
	v_add_f32_e32 v22, v124, v126
	v_lshlrev_b32_e32 v127, 16, v234
	v_mul_f32_e32 v22, v22, v127
	v_mul_f32_e32 v126, v87, v120
	v_fmac_f32_e32 v126, v23, v83
	v_add_f32_e32 v23, v124, v126
	v_and_b32_e32 v127, 0xffff0000, v234
	v_mul_f32_e32 v23, v23, v127
	v_mul_f32_e32 v126, v88, v120
	v_fmac_f32_e32 v126, v24, v84
	v_add_f32_e32 v24, v124, v126
	v_lshlrev_b32_e32 v127, 16, v235
	v_mul_f32_e32 v24, v24, v127
	v_mul_f32_e32 v126, v89, v120
	v_fmac_f32_e32 v126, v25, v85
	v_add_f32_e32 v25, v124, v126
	v_and_b32_e32 v127, 0xffff0000, v235
	v_mul_f32_e32 v25, v25, v127
	v_cvt_pk_bf16_f32 v22, v22, v23
	v_cvt_pk_bf16_f32 v23, v24, v25
	ds_write_b64 v129, v[22:23] offset:4096
	v_mul_f32_e32 v126, v78, v120
	v_fmac_f32_e32 v126, v26, v74
	v_add_f32_e32 v26, v124, v126
	v_lshlrev_b32_e32 v127, 16, v236
	v_mul_f32_e32 v26, v26, v127
	v_mul_f32_e32 v126, v79, v120
	v_fmac_f32_e32 v126, v27, v75
	v_add_f32_e32 v27, v124, v126
	v_and_b32_e32 v127, 0xffff0000, v236
	v_mul_f32_e32 v27, v27, v127
	v_mul_f32_e32 v126, v80, v120
	v_fmac_f32_e32 v126, v28, v76
	v_add_f32_e32 v28, v124, v126
	v_lshlrev_b32_e32 v127, 16, v237
	v_mul_f32_e32 v28, v28, v127
	v_mul_f32_e32 v126, v81, v120
	v_fmac_f32_e32 v126, v29, v77
	v_add_f32_e32 v29, v124, v126
	v_and_b32_e32 v127, 0xffff0000, v237
	v_mul_f32_e32 v29, v29, v127
	v_cvt_pk_bf16_f32 v26, v26, v27
	v_cvt_pk_bf16_f32 v27, v28, v29
	ds_write_b64 v130, v[26:27] offset:4096
	v_mul_f32_e32 v126, v70, v120
	v_fmac_f32_e32 v126, v30, v66
	v_add_f32_e32 v30, v124, v126
	v_lshlrev_b32_e32 v127, 16, v238
	v_mul_f32_e32 v30, v30, v127
	v_mul_f32_e32 v126, v71, v120
	v_fmac_f32_e32 v126, v31, v67
	v_add_f32_e32 v31, v124, v126
	v_and_b32_e32 v127, 0xffff0000, v238
	v_mul_f32_e32 v31, v31, v127
	v_mul_f32_e32 v126, v72, v120
	v_fmac_f32_e32 v126, v32, v68
	v_add_f32_e32 v32, v124, v126
	v_lshlrev_b32_e32 v127, 16, v239
	v_mul_f32_e32 v32, v32, v127
	v_mul_f32_e32 v126, v73, v120
	v_fmac_f32_e32 v126, v33, v69
	v_add_f32_e32 v33, v124, v126
	v_and_b32_e32 v127, 0xffff0000, v239
	v_mul_f32_e32 v33, v33, v127
	v_cvt_pk_bf16_f32 v30, v30, v31
	v_cvt_pk_bf16_f32 v31, v32, v33
	ds_write_b64 v131, v[30:31] offset:4096
	v_mul_f32_e32 v126, v94, v121
	v_fmac_f32_e32 v126, v2, v90
	v_add_f32_e32 v2, v125, v126
	v_lshlrev_b32_e32 v127, 16, v252
	v_mul_f32_e32 v2, v2, v127
	v_mul_f32_e32 v126, v95, v121
	v_fmac_f32_e32 v126, v3, v91
	v_add_f32_e32 v3, v125, v126
	v_and_b32_e32 v127, 0xffff0000, v252
	v_mul_f32_e32 v3, v3, v127
	v_mul_f32_e32 v126, v96, v121
	v_fmac_f32_e32 v126, v4, v92
	v_add_f32_e32 v4, v125, v126
	v_lshlrev_b32_e32 v127, 16, v253
	v_mul_f32_e32 v4, v4, v127
	v_mul_f32_e32 v126, v97, v121
	v_fmac_f32_e32 v126, v5, v93
	v_add_f32_e32 v5, v125, v126
	v_and_b32_e32 v127, 0xffff0000, v253
	v_mul_f32_e32 v5, v5, v127
	v_cvt_pk_bf16_f32 v2, v2, v3
	v_cvt_pk_bf16_f32 v3, v4, v5
	ds_write_b64 v128, v[2:3] offset:6144
	v_mul_f32_e32 v126, v86, v121
	v_fmac_f32_e32 v126, v6, v82
	v_add_f32_e32 v6, v125, v126
	v_lshlrev_b32_e32 v127, 16, v254
	v_mul_f32_e32 v6, v6, v127
	v_mul_f32_e32 v126, v87, v121
	v_fmac_f32_e32 v126, v7, v83
	v_add_f32_e32 v7, v125, v126
	v_and_b32_e32 v127, 0xffff0000, v254
	v_mul_f32_e32 v7, v7, v127
	v_mul_f32_e32 v126, v88, v121
	v_fmac_f32_e32 v126, v8, v84
	v_add_f32_e32 v8, v125, v126
	v_lshlrev_b32_e32 v127, 16, v255
	v_mul_f32_e32 v8, v8, v127
	v_mul_f32_e32 v126, v89, v121
	v_fmac_f32_e32 v126, v9, v85
	v_add_f32_e32 v9, v125, v126
	v_and_b32_e32 v127, 0xffff0000, v255
	v_mul_f32_e32 v9, v9, v127
	v_cvt_pk_bf16_f32 v6, v6, v7
	v_cvt_pk_bf16_f32 v7, v8, v9
	ds_write_b64 v129, v[6:7] offset:6144
	v_mul_f32_e32 v126, v78, v121
	v_fmac_f32_e32 v126, v10, v74
	v_add_f32_e32 v10, v125, v126
	v_lshlrev_b32_e32 v127, 16, v240
	v_mul_f32_e32 v10, v10, v127
	v_mul_f32_e32 v126, v79, v121
	v_fmac_f32_e32 v126, v11, v75
	v_add_f32_e32 v11, v125, v126
	v_and_b32_e32 v127, 0xffff0000, v240
	v_mul_f32_e32 v11, v11, v127
	v_mul_f32_e32 v126, v80, v121
	v_fmac_f32_e32 v126, v12, v76
	v_add_f32_e32 v12, v125, v126
	v_lshlrev_b32_e32 v127, 16, v241
	v_mul_f32_e32 v12, v12, v127
	v_mul_f32_e32 v126, v81, v121
	v_fmac_f32_e32 v126, v13, v77
	v_add_f32_e32 v13, v125, v126
	v_and_b32_e32 v127, 0xffff0000, v241
	v_mul_f32_e32 v13, v13, v127
	v_cvt_pk_bf16_f32 v10, v10, v11
	v_cvt_pk_bf16_f32 v11, v12, v13
	ds_write_b64 v130, v[10:11] offset:6144
	v_mul_f32_e32 v126, v70, v121
	v_fmac_f32_e32 v126, v14, v66
	v_add_f32_e32 v14, v125, v126
	v_lshlrev_b32_e32 v127, 16, v246
	v_mul_f32_e32 v14, v14, v127
	v_mul_f32_e32 v126, v71, v121
	v_fmac_f32_e32 v126, v15, v67
	v_add_f32_e32 v15, v125, v126
	v_and_b32_e32 v127, 0xffff0000, v246
	v_mul_f32_e32 v15, v15, v127
	v_mul_f32_e32 v126, v72, v121
	v_fmac_f32_e32 v126, v16, v68
	v_add_f32_e32 v16, v125, v126
	v_lshlrev_b32_e32 v127, 16, v247
	v_mul_f32_e32 v16, v16, v127
	v_mul_f32_e32 v126, v73, v121
	v_fmac_f32_e32 v126, v17, v69
	v_add_f32_e32 v17, v125, v126
	v_and_b32_e32 v127, 0xffff0000, v247
	v_mul_f32_e32 v17, v17, v127
	v_cvt_pk_bf16_f32 v14, v14, v15
	v_cvt_pk_bf16_f32 v15, v16, v17
	ds_write_b64 v131, v[14:15] offset:6144
	s_waitcnt lgkmcnt(0)
	ds_read_b128 v[2:5], v132 offset:0
	ds_read_b128 v[6:9], v132 offset:1024
	ds_read_b128 v[10:13], v132 offset:2048
	ds_read_b128 v[14:17], v132 offset:3072
	ds_read_b128 v[18:21], v132 offset:4096
	ds_read_b128 v[22:25], v132 offset:5120
	ds_read_b128 v[26:29], v132 offset:6144
	ds_read_b128 v[30:33], v132 offset:7168
	s_waitcnt lgkmcnt(7)
	global_store_dwordx4 v133, v[2:5], s[62:63] offset:1536
	v_add_u32_e32 v127, 0x8000, v133
	s_waitcnt lgkmcnt(6)
	global_store_dwordx4 v127, v[6:9], s[62:63] offset:1536
	v_add_u32_e32 v126, 0x10000, v133
	s_waitcnt lgkmcnt(5)
	global_store_dwordx4 v126, v[10:13], s[62:63] offset:1536
	v_add_u32_e32 v127, 0x18000, v133
	s_waitcnt lgkmcnt(4)
	global_store_dwordx4 v127, v[14:17], s[62:63] offset:1536
	v_add_u32_e32 v126, 0x20000, v133
	s_waitcnt lgkmcnt(3)
	global_store_dwordx4 v126, v[18:21], s[62:63] offset:1536
	v_add_u32_e32 v127, 0x28000, v133
	s_waitcnt lgkmcnt(2)
	global_store_dwordx4 v127, v[22:25], s[62:63] offset:1536
	v_add_u32_e32 v126, 0x30000, v133
	s_waitcnt lgkmcnt(1)
	global_store_dwordx4 v126, v[26:29], s[62:63] offset:1536
	v_add_u32_e32 v127, 0x38000, v133
	s_waitcnt lgkmcnt(0)
	global_store_dwordx4 v127, v[30:33], s[62:63] offset:1536
	s_barrier
	s_cbranch_scc0 .LBB0_849
